# att softmax: batched LDS reads branch-free; sel score loop: drop redundant canonicalizing v_max
# speedup vs baseline: 1.0183x; 1.0183x over previous
.LBB0_820:
	s_add_i32 s40, s8, -3
	s_min_i32 s9, s40, s7
	s_waitcnt vmcnt(13)
	v_lshl_add_u32 v56, s9, 8, v102
	v_ashrrev_i32_e32 v57, 31, v56
	v_lshlrev_b64 v[56:57], 7, v[56:57]
	s_waitcnt vmcnt(12)
	v_lshl_add_u64 v[60:61], v[100:101], 0, v[56:57]
	global_load_dwordx4 v[88:91], v[60:61], off
	global_load_dwordx4 v[92:95], v[60:61], off offset:1024
	global_load_dwordx4 v[56:59], v[60:61], off offset:2048
	s_nop 0
	global_load_dwordx4 v[60:63], v[60:61], off offset:3072
	v_add_u32_e32 v103, v178, v98
	s_waitcnt vmcnt(15)
	ds_write_b128 v103, v[64:67]
	s_waitcnt vmcnt(14)
	ds_write_b128 v103, v[68:71] offset:1152
	v_add_u32_e32 v107, v179, v96
	ds_read_b128 v[64:67], v107
	ds_read_b128 v[68:71], v107 offset:64
	s_waitcnt lgkmcnt(1)
	v_mfma_f32_16x16x32_bf16 v[108:111], v[0:3], v[64:67], 0
	v_mfma_f32_16x16x32_bf16 v[112:115], v[8:11], v[64:67], 0
	s_waitcnt lgkmcnt(0)
	v_mfma_f32_16x16x32_bf16 v[108:111], v[4:7], v[68:71], v[108:111]
	v_mfma_f32_16x16x32_bf16 v[112:115], v[12:15], v[68:71], v[112:115]
	v_mfma_f32_16x16x32_bf16 v[116:119], v[16:19], v[64:67], 0
	s_nop 5
	v_max_f32_e32 v108, 0, v108
	v_fma_f32 v120, v162, v108, 0
	v_max_f32_e32 v108, 0, v109
	v_max_f32_e32 v112, 0, v112
	v_fmac_f32_e32 v120, v163, v108
	v_fma_f32 v112, v166, v112, 0
	v_max_f32_e32 v108, 0, v113
	v_fmac_f32_e32 v112, v167, v108
	v_max_f32_e32 v108, 0, v110
	v_fmac_f32_e32 v120, v164, v108
	v_mfma_f32_16x16x32_bf16 v[64:67], v[24:27], v[64:67], 0
	v_max_f32_e32 v108, 0, v114
	v_fmac_f32_e32 v112, v168, v108
	v_max_f32_e32 v108, 0, v111
	v_fmac_f32_e32 v120, v165, v108
	v_mfma_f32_16x16x32_bf16 v[64:67], v[28:31], v[68:71], v[64:67]
	v_max_f32_e32 v113, 0, v115
	v_fmac_f32_e32 v112, v169, v113
	v_add_f32_e32 v112, v120, v112
	v_mfma_f32_16x16x32_bf16 v[108:111], v[20:23], v[68:71], v[116:119]
	ds_write_b32 v99, v112
	s_nop 2
	v_max_f32_e32 v64, 0, v64
	v_fma_f32 v64, v174, v64, 0
	s_nop 1
	v_max_f32_e32 v68, 0, v108
	v_max_f32_e32 v65, 0, v65
	v_fma_f32 v68, v170, v68, 0
	v_max_f32_e32 v69, 0, v109
	v_fmac_f32_e32 v64, v175, v65
	v_fmac_f32_e32 v68, v171, v69
	v_max_f32_e32 v65, 0, v110
	v_fmac_f32_e32 v68, v172, v65
	v_max_f32_e32 v65, 0, v66
	v_fmac_f32_e32 v64, v176, v65
	v_max_f32_e32 v65, 0, v111
	v_fmac_f32_e32 v68, v173, v65
	v_max_f32_e32 v65, 0, v67
	v_fmac_f32_e32 v64, v177, v65
	v_add_f32_e32 v64, v68, v64
	v_add_u32_e32 v65, 0x10000, v99
	ds_write_b32 v65, v64
	s_waitcnt vmcnt(13)
	ds_write_b128 v103, v[32:35]
	s_waitcnt vmcnt(12)
	ds_write_b128 v103, v[36:39] offset:1152
	ds_read_b128 v[32:35], v107
	ds_read_b128 v[36:39], v107 offset:64
	s_waitcnt lgkmcnt(1)
	v_mfma_f32_16x16x32_bf16 v[64:67], v[0:3], v[32:35], 0
	v_mfma_f32_16x16x32_bf16 v[68:71], v[8:11], v[32:35], 0
	s_waitcnt lgkmcnt(0)
	v_mfma_f32_16x16x32_bf16 v[64:67], v[4:7], v[36:39], v[64:67]
	v_mfma_f32_16x16x32_bf16 v[68:71], v[12:15], v[36:39], v[68:71]
	v_mfma_f32_16x16x32_bf16 v[108:111], v[16:19], v[32:35], 0
	s_nop 5
	v_max_f32_e32 v64, 0, v64
	v_fma_f32 v112, v162, v64, 0
	v_max_f32_e32 v64, 0, v68
	v_fma_f32 v68, v166, v64, 0
	v_max_f32_e32 v64, 0, v65
	v_fmac_f32_e32 v112, v163, v64
	v_max_f32_e32 v64, 0, v69
	v_fmac_f32_e32 v68, v167, v64
	v_max_f32_e32 v64, 0, v66
	v_fmac_f32_e32 v112, v164, v64
	v_mfma_f32_16x16x32_bf16 v[32:35], v[24:27], v[32:35], 0
	v_max_f32_e32 v64, 0, v70
	v_fmac_f32_e32 v68, v168, v64
	v_max_f32_e32 v64, 0, v67
	v_fmac_f32_e32 v112, v165, v64
	v_mfma_f32_16x16x32_bf16 v[32:35], v[28:31], v[36:39], v[32:35]
	v_max_f32_e32 v69, 0, v71
	v_fmac_f32_e32 v68, v169, v69
	v_add_f32_e32 v68, v112, v68
	v_mfma_f32_16x16x32_bf16 v[64:67], v[20:23], v[36:39], v[108:111]
	ds_write_b32 v99, v68 offset:64
	s_nop 2
	v_max_f32_e32 v32, 0, v32
	v_fma_f32 v32, v174, v32, 0
	s_nop 1
	v_max_f32_e32 v36, 0, v64
	v_max_f32_e32 v33, 0, v33
	v_fma_f32 v36, v170, v36, 0
	v_max_f32_e32 v37, 0, v65
	v_fmac_f32_e32 v32, v175, v33
	v_fmac_f32_e32 v36, v171, v37
	v_max_f32_e32 v33, 0, v66
	v_fmac_f32_e32 v36, v172, v33
	v_max_f32_e32 v33, 0, v34
	v_fmac_f32_e32 v32, v176, v33
	v_max_f32_e32 v33, 0, v67
	v_fmac_f32_e32 v36, v173, v33
	v_max_f32_e32 v33, 0, v35
	v_fmac_f32_e32 v32, v177, v33
	v_add_f32_e32 v32, v36, v32
	v_add_u32_e32 v33, 0x10040, v99
	ds_write_b32 v33, v32
	s_add_i32 s9, s8, -2
	s_min_i32 s57, s9, s7
	v_lshl_add_u32 v32, s57, 8, v102
	v_ashrrev_i32_e32 v33, 31, v32
	v_lshlrev_b64 v[32:33], 7, v[32:33]
	v_lshl_add_u64 v[36:37], v[100:101], 0, v[32:33]
	global_load_dwordx4 v[64:67], v[36:37], off
	global_load_dwordx4 v[68:71], v[36:37], off offset:1024
	global_load_dwordx4 v[32:35], v[36:37], off offset:2048
	s_nop 0
	global_load_dwordx4 v[36:39], v[36:37], off offset:3072
	s_add_i32 s57, s8, -5
	s_cmp_ge_i32 s57, s6
	s_cbranch_scc1 .LBB0_822
	s_waitcnt vmcnt(15)
	ds_write_b128 v103, v[72:75]
	s_waitcnt vmcnt(14)
	ds_write_b128 v103, v[76:79] offset:1152
	ds_read_b128 v[72:75], v107
	ds_read_b128 v[76:79], v107 offset:64
	s_waitcnt lgkmcnt(1)
	v_mfma_f32_16x16x32_bf16 v[108:111], v[0:3], v[72:75], 0
	v_mfma_f32_16x16x32_bf16 v[112:115], v[8:11], v[72:75], 0
	s_waitcnt lgkmcnt(0)
	v_mfma_f32_16x16x32_bf16 v[108:111], v[4:7], v[76:79], v[108:111]
	v_mfma_f32_16x16x32_bf16 v[112:115], v[12:15], v[76:79], v[112:115]
	v_mfma_f32_16x16x32_bf16 v[116:119], v[16:19], v[72:75], 0
	s_nop 5
	v_max_f32_e32 v108, 0, v108
	v_fma_f32 v120, v162, v108, 0
	v_max_f32_e32 v108, 0, v109
	v_max_f32_e32 v112, 0, v112
	v_fmac_f32_e32 v120, v163, v108
	v_fma_f32 v112, v166, v112, 0
	v_max_f32_e32 v108, 0, v113
	v_fmac_f32_e32 v112, v167, v108
	v_max_f32_e32 v108, 0, v110
	v_fmac_f32_e32 v120, v164, v108
	v_mfma_f32_16x16x32_bf16 v[72:75], v[24:27], v[72:75], 0
	v_max_f32_e32 v108, 0, v114
	v_fmac_f32_e32 v112, v168, v108
	v_max_f32_e32 v108, 0, v111
	v_fmac_f32_e32 v120, v165, v108
	v_mfma_f32_16x16x32_bf16 v[72:75], v[28:31], v[76:79], v[72:75]
	v_max_f32_e32 v113, 0, v115
	v_fmac_f32_e32 v112, v169, v113
	v_add_f32_e32 v112, v120, v112
	v_mfma_f32_16x16x32_bf16 v[108:111], v[20:23], v[76:79], v[116:119]
	ds_write_b32 v99, v112 offset:1024
	s_nop 2
	v_max_f32_e32 v72, 0, v72
	v_fma_f32 v72, v174, v72, 0
	s_nop 1
	v_max_f32_e32 v76, 0, v108
	v_max_f32_e32 v73, 0, v73
	v_fma_f32 v76, v170, v76, 0
	v_max_f32_e32 v77, 0, v109
	v_fmac_f32_e32 v72, v175, v73
	v_fmac_f32_e32 v76, v171, v77
	v_max_f32_e32 v73, 0, v110
	v_fmac_f32_e32 v76, v172, v73
	v_max_f32_e32 v73, 0, v74
	v_fmac_f32_e32 v72, v176, v73
	v_max_f32_e32 v73, 0, v111
	v_fmac_f32_e32 v76, v173, v73
	v_max_f32_e32 v73, 0, v75
	v_fmac_f32_e32 v72, v177, v73
	v_add_f32_e32 v72, v76, v72
	v_add_u32_e32 v73, 0x10400, v99
	ds_write_b32 v73, v72
	s_waitcnt vmcnt(13)
	ds_write_b128 v103, v[40:43]
	s_waitcnt vmcnt(12)
	ds_write_b128 v103, v[44:47] offset:1152
	ds_read_b128 v[40:43], v107
	ds_read_b128 v[44:47], v107 offset:64
	s_waitcnt lgkmcnt(1)
	v_mfma_f32_16x16x32_bf16 v[72:75], v[0:3], v[40:43], 0
	v_mfma_f32_16x16x32_bf16 v[76:79], v[8:11], v[40:43], 0
	s_waitcnt lgkmcnt(0)
	v_mfma_f32_16x16x32_bf16 v[72:75], v[4:7], v[44:47], v[72:75]
	v_mfma_f32_16x16x32_bf16 v[76:79], v[12:15], v[44:47], v[76:79]
	v_mfma_f32_16x16x32_bf16 v[108:111], v[16:19], v[40:43], 0
	s_nop 5
	v_max_f32_e32 v72, 0, v72
	v_fma_f32 v112, v162, v72, 0
	v_max_f32_e32 v72, 0, v76
	v_fma_f32 v76, v166, v72, 0
	v_max_f32_e32 v72, 0, v73
	v_fmac_f32_e32 v112, v163, v72
	v_max_f32_e32 v72, 0, v77
	v_fmac_f32_e32 v76, v167, v72
	v_max_f32_e32 v72, 0, v74
	v_fmac_f32_e32 v112, v164, v72
	v_mfma_f32_16x16x32_bf16 v[40:43], v[24:27], v[40:43], 0
	v_max_f32_e32 v72, 0, v78
	v_fmac_f32_e32 v76, v168, v72
	v_max_f32_e32 v72, 0, v75
	v_fmac_f32_e32 v112, v165, v72
	v_mfma_f32_16x16x32_bf16 v[40:43], v[28:31], v[44:47], v[40:43]
	v_max_f32_e32 v77, 0, v79
	v_fmac_f32_e32 v76, v169, v77
	v_add_f32_e32 v76, v112, v76
	v_mfma_f32_16x16x32_bf16 v[72:75], v[20:23], v[44:47], v[108:111]
	ds_write_b32 v99, v76 offset:1088
	s_nop 2
	v_max_f32_e32 v40, 0, v40
	v_fma_f32 v40, v174, v40, 0
	s_nop 1
	v_max_f32_e32 v44, 0, v72
	v_max_f32_e32 v41, 0, v41
	v_fma_f32 v44, v170, v44, 0
	v_max_f32_e32 v45, 0, v73
	v_fmac_f32_e32 v40, v175, v41
	v_fmac_f32_e32 v44, v171, v45
	v_max_f32_e32 v41, 0, v74
	v_fmac_f32_e32 v44, v172, v41
	v_max_f32_e32 v41, 0, v42
	v_fmac_f32_e32 v40, v176, v41
	v_max_f32_e32 v41, 0, v75
	v_fmac_f32_e32 v44, v173, v41
	v_max_f32_e32 v41, 0, v43
	v_fmac_f32_e32 v40, v177, v41
	v_add_f32_e32 v40, v44, v40
	v_add_u32_e32 v41, 0x10440, v99
	ds_write_b32 v41, v40
.LBB0_822:
	s_add_i32 s57, s8, -1
	s_min_i32 s57, s57, s7
	s_waitcnt vmcnt(13)
	v_lshl_add_u32 v40, s57, 8, v102
	v_ashrrev_i32_e32 v41, 31, v40
	v_lshlrev_b64 v[40:41], 7, v[40:41]
	s_waitcnt vmcnt(12)
	v_lshl_add_u64 v[44:45], v[100:101], 0, v[40:41]
	global_load_dwordx4 v[72:75], v[44:45], off
	global_load_dwordx4 v[76:79], v[44:45], off offset:1024
	global_load_dwordx4 v[40:43], v[44:45], off offset:2048
	s_nop 0
	global_load_dwordx4 v[44:47], v[44:45], off offset:3072
	s_add_i32 s57, s8, -4
	s_cmp_ge_i32 s57, s6
	s_cbranch_scc1 .LBB0_824
	s_waitcnt vmcnt(15)
	ds_write_b128 v103, v[80:83]
	s_waitcnt vmcnt(14)
	ds_write_b128 v103, v[84:87] offset:1152
	ds_read_b128 v[80:83], v107
	ds_read_b128 v[84:87], v107 offset:64
	s_waitcnt lgkmcnt(1)
	v_mfma_f32_16x16x32_bf16 v[108:111], v[0:3], v[80:83], 0
	v_mfma_f32_16x16x32_bf16 v[112:115], v[8:11], v[80:83], 0
	s_waitcnt lgkmcnt(0)
	v_mfma_f32_16x16x32_bf16 v[108:111], v[4:7], v[84:87], v[108:111]
	v_mfma_f32_16x16x32_bf16 v[112:115], v[12:15], v[84:87], v[112:115]
	v_mfma_f32_16x16x32_bf16 v[116:119], v[16:19], v[80:83], 0
	s_nop 5
	v_max_f32_e32 v108, 0, v108
	v_fma_f32 v120, v162, v108, 0
	v_max_f32_e32 v108, 0, v109
	v_max_f32_e32 v112, 0, v112
	v_fmac_f32_e32 v120, v163, v108
	v_fma_f32 v112, v166, v112, 0
	v_max_f32_e32 v108, 0, v113
	v_fmac_f32_e32 v112, v167, v108
	v_max_f32_e32 v108, 0, v110
	v_fmac_f32_e32 v120, v164, v108
	v_mfma_f32_16x16x32_bf16 v[80:83], v[24:27], v[80:83], 0
	v_max_f32_e32 v108, 0, v114
	v_fmac_f32_e32 v112, v168, v108
	v_max_f32_e32 v108, 0, v111
	v_fmac_f32_e32 v120, v165, v108
	v_mfma_f32_16x16x32_bf16 v[80:83], v[28:31], v[84:87], v[80:83]
	v_max_f32_e32 v113, 0, v115
	v_fmac_f32_e32 v112, v169, v113
	v_add_f32_e32 v112, v120, v112
	v_mfma_f32_16x16x32_bf16 v[108:111], v[20:23], v[84:87], v[116:119]
	ds_write_b32 v99, v112 offset:2048
	s_nop 2
	v_max_f32_e32 v80, 0, v80
	v_fma_f32 v80, v174, v80, 0
	s_nop 1
	v_max_f32_e32 v84, 0, v108
	v_max_f32_e32 v81, 0, v81
	v_fma_f32 v84, v170, v84, 0
	v_max_f32_e32 v85, 0, v109
	v_fmac_f32_e32 v80, v175, v81
	v_fmac_f32_e32 v84, v171, v85
	v_max_f32_e32 v81, 0, v110
	v_fmac_f32_e32 v84, v172, v81
	v_max_f32_e32 v81, 0, v82
	v_fmac_f32_e32 v80, v176, v81
	v_max_f32_e32 v81, 0, v111
	v_fmac_f32_e32 v84, v173, v81
	v_max_f32_e32 v81, 0, v83
	v_fmac_f32_e32 v80, v177, v81
	v_add_f32_e32 v80, v84, v80
	v_add_u32_e32 v81, 0x10800, v99
	ds_write_b32 v81, v80
	s_waitcnt vmcnt(13)
	ds_write_b128 v103, v[48:51]
	s_waitcnt vmcnt(12)
	ds_write_b128 v103, v[52:55] offset:1152
	ds_read_b128 v[48:51], v107
	ds_read_b128 v[52:55], v107 offset:64
	s_waitcnt lgkmcnt(1)
	v_mfma_f32_16x16x32_bf16 v[80:83], v[0:3], v[48:51], 0
	v_mfma_f32_16x16x32_bf16 v[84:87], v[8:11], v[48:51], 0
	s_waitcnt lgkmcnt(0)
	v_mfma_f32_16x16x32_bf16 v[80:83], v[4:7], v[52:55], v[80:83]
	v_mfma_f32_16x16x32_bf16 v[84:87], v[12:15], v[52:55], v[84:87]
	v_mfma_f32_16x16x32_bf16 v[108:111], v[16:19], v[48:51], 0
	s_nop 5
	v_max_f32_e32 v80, 0, v80
	v_fma_f32 v112, v162, v80, 0
	v_max_f32_e32 v80, 0, v84
	v_fma_f32 v84, v166, v80, 0
	v_max_f32_e32 v80, 0, v81
	v_fmac_f32_e32 v112, v163, v80
	v_max_f32_e32 v80, 0, v85
	v_fmac_f32_e32 v84, v167, v80
	v_max_f32_e32 v80, 0, v82
	v_fmac_f32_e32 v112, v164, v80
	v_mfma_f32_16x16x32_bf16 v[48:51], v[24:27], v[48:51], 0
	v_max_f32_e32 v80, 0, v86
	v_fmac_f32_e32 v84, v168, v80
	v_max_f32_e32 v80, 0, v83
	v_fmac_f32_e32 v112, v165, v80
	v_mfma_f32_16x16x32_bf16 v[48:51], v[28:31], v[52:55], v[48:51]
	v_max_f32_e32 v85, 0, v87
	v_fmac_f32_e32 v84, v169, v85
	v_add_f32_e32 v84, v112, v84
	v_mfma_f32_16x16x32_bf16 v[80:83], v[20:23], v[52:55], v[108:111]
	ds_write_b32 v99, v84 offset:2112
	s_nop 2
	v_max_f32_e32 v48, 0, v48
	v_fma_f32 v48, v174, v48, 0
	s_nop 1
	v_max_f32_e32 v52, 0, v80
	v_max_f32_e32 v49, 0, v49
	v_fma_f32 v52, v170, v52, 0
	v_max_f32_e32 v53, 0, v81
	v_fmac_f32_e32 v48, v175, v49
	v_fmac_f32_e32 v52, v171, v53
	v_max_f32_e32 v49, 0, v82
	v_fmac_f32_e32 v52, v172, v49
	v_max_f32_e32 v49, 0, v50
	v_fmac_f32_e32 v48, v176, v49
	v_max_f32_e32 v49, 0, v83
	v_fmac_f32_e32 v52, v173, v49
	v_max_f32_e32 v49, 0, v51
	v_fmac_f32_e32 v48, v177, v49
	v_add_f32_e32 v48, v52, v48
	v_add_u32_e32 v49, 0x10840, v99
	ds_write_b32 v49, v48
.LBB0_824:
	s_min_i32 s57, s8, s7
	s_cmp_ge_i32 s40, s6
	s_waitcnt vmcnt(13)
	v_lshl_add_u32 v48, s57, 8, v102
	v_ashrrev_i32_e32 v49, 31, v48
	v_lshlrev_b64 v[48:49], 7, v[48:49]
	s_waitcnt vmcnt(12)
	v_lshl_add_u64 v[52:53], v[100:101], 0, v[48:49]
	global_load_dwordx4 v[80:83], v[52:53], off
	global_load_dwordx4 v[84:87], v[52:53], off offset:1024
	global_load_dwordx4 v[48:51], v[52:53], off offset:2048
	s_nop 0
	global_load_dwordx4 v[52:55], v[52:53], off offset:3072
	s_cbranch_scc1 .LBB0_819
	s_waitcnt vmcnt(15)
	ds_write_b128 v103, v[88:91]
	s_waitcnt vmcnt(14)
	ds_write_b128 v103, v[92:95] offset:1152
	ds_read_b128 v[88:91], v107
	ds_read_b128 v[92:95], v107 offset:64
	s_waitcnt lgkmcnt(1)
	v_mfma_f32_16x16x32_bf16 v[108:111], v[0:3], v[88:91], 0
	v_mfma_f32_16x16x32_bf16 v[112:115], v[8:11], v[88:91], 0
	s_waitcnt lgkmcnt(0)
	v_mfma_f32_16x16x32_bf16 v[108:111], v[4:7], v[92:95], v[108:111]
	v_mfma_f32_16x16x32_bf16 v[112:115], v[12:15], v[92:95], v[112:115]
	v_mfma_f32_16x16x32_bf16 v[116:119], v[16:19], v[88:91], 0
	s_nop 5
	v_max_f32_e32 v108, 0, v108
	v_fma_f32 v120, v162, v108, 0
	v_max_f32_e32 v108, 0, v109
	v_max_f32_e32 v112, 0, v112
	v_fmac_f32_e32 v120, v163, v108
	v_fma_f32 v112, v166, v112, 0
	v_max_f32_e32 v108, 0, v113
	v_fmac_f32_e32 v112, v167, v108
	v_max_f32_e32 v108, 0, v110
	v_fmac_f32_e32 v120, v164, v108
	v_mfma_f32_16x16x32_bf16 v[88:91], v[24:27], v[88:91], 0
	v_max_f32_e32 v108, 0, v114
	v_fmac_f32_e32 v112, v168, v108
	v_max_f32_e32 v108, 0, v111
	v_fmac_f32_e32 v120, v165, v108
	v_mfma_f32_16x16x32_bf16 v[88:91], v[28:31], v[92:95], v[88:91]
	v_max_f32_e32 v113, 0, v115
	v_fmac_f32_e32 v112, v169, v113
	v_add_f32_e32 v112, v120, v112
	v_mfma_f32_16x16x32_bf16 v[108:111], v[20:23], v[92:95], v[116:119]
	ds_write_b32 v99, v112 offset:3072
	s_nop 2
	v_max_f32_e32 v88, 0, v88
	v_fma_f32 v88, v174, v88, 0
	s_nop 1
	v_max_f32_e32 v92, 0, v108
	v_max_f32_e32 v89, 0, v89
	v_fma_f32 v92, v170, v92, 0
	v_max_f32_e32 v93, 0, v109
	v_fmac_f32_e32 v88, v175, v89
	v_fmac_f32_e32 v92, v171, v93
	v_max_f32_e32 v89, 0, v110
	v_fmac_f32_e32 v92, v172, v89
	v_max_f32_e32 v89, 0, v90
	v_fmac_f32_e32 v88, v176, v89
	v_max_f32_e32 v89, 0, v111
	v_fmac_f32_e32 v92, v173, v89
	v_max_f32_e32 v89, 0, v91
	v_fmac_f32_e32 v88, v177, v89
	v_add_f32_e32 v88, v92, v88
	v_add_u32_e32 v89, 0x10c00, v99
	ds_write_b32 v89, v88
	s_waitcnt vmcnt(13)
	ds_write_b128 v103, v[56:59]
	s_waitcnt vmcnt(12)
	ds_write_b128 v103, v[60:63] offset:1152
	ds_read_b128 v[56:59], v107
	ds_read_b128 v[60:63], v107 offset:64
	s_waitcnt lgkmcnt(1)
	v_mfma_f32_16x16x32_bf16 v[88:91], v[0:3], v[56:59], 0
	v_mfma_f32_16x16x32_bf16 v[92:95], v[8:11], v[56:59], 0
	s_waitcnt lgkmcnt(0)
	v_mfma_f32_16x16x32_bf16 v[88:91], v[4:7], v[60:63], v[88:91]
	v_mfma_f32_16x16x32_bf16 v[92:95], v[12:15], v[60:63], v[92:95]
	v_mfma_f32_16x16x32_bf16 v[108:111], v[16:19], v[56:59], 0
	s_nop 5
	v_max_f32_e32 v88, 0, v88
	v_fma_f32 v103, v162, v88, 0
	v_max_f32_e32 v88, 0, v92
	v_fma_f32 v92, v166, v88, 0
	v_max_f32_e32 v88, 0, v89
	v_fmac_f32_e32 v103, v163, v88
	v_max_f32_e32 v88, 0, v93
	v_fmac_f32_e32 v92, v167, v88
	v_max_f32_e32 v88, 0, v90
	v_fmac_f32_e32 v103, v164, v88
	v_mfma_f32_16x16x32_bf16 v[56:59], v[24:27], v[56:59], 0
	v_max_f32_e32 v88, 0, v94
	v_fmac_f32_e32 v92, v168, v88
	v_max_f32_e32 v88, 0, v91
	v_fmac_f32_e32 v103, v165, v88
	v_mfma_f32_16x16x32_bf16 v[56:59], v[28:31], v[60:63], v[56:59]
	v_max_f32_e32 v93, 0, v95
	v_fmac_f32_e32 v92, v169, v93
	v_add_f32_e32 v92, v103, v92
	v_mfma_f32_16x16x32_bf16 v[88:91], v[20:23], v[60:63], v[108:111]
	ds_write_b32 v99, v92 offset:3136
	s_nop 2
	v_max_f32_e32 v56, 0, v56
	v_fma_f32 v56, v174, v56, 0
	s_nop 1
	v_max_f32_e32 v60, 0, v88
	v_max_f32_e32 v57, 0, v57
	v_fma_f32 v60, v170, v60, 0
	v_max_f32_e32 v61, 0, v89
	v_fmac_f32_e32 v56, v175, v57
	v_fmac_f32_e32 v60, v171, v61
	v_max_f32_e32 v57, 0, v90
	v_fmac_f32_e32 v60, v172, v57
	v_max_f32_e32 v57, 0, v58
	v_fmac_f32_e32 v56, v176, v57
	v_max_f32_e32 v57, 0, v91
	v_fmac_f32_e32 v60, v173, v57
	v_max_f32_e32 v57, 0, v59
	v_fmac_f32_e32 v56, v177, v57
	v_add_f32_e32 v56, v60, v56
	v_add_u32_e32 v57, 0x10c40, v99
	ds_write_b32 v57, v56
	s_branch .LBB0_819

.LBB0_834:
	s_add_i32 s40, s8, -3
	s_min_i32 s9, s40, s7
	s_waitcnt vmcnt(13)
	v_lshl_add_u32 v56, s9, 8, v102
	v_ashrrev_i32_e32 v57, 31, v56
	v_lshlrev_b64 v[56:57], 7, v[56:57]
	s_waitcnt vmcnt(12)
	v_lshl_add_u64 v[60:61], v[100:101], 0, v[56:57]
	global_load_dwordx4 v[88:91], v[60:61], off
	global_load_dwordx4 v[92:95], v[60:61], off offset:1024
	global_load_dwordx4 v[56:59], v[60:61], off offset:2048
	s_nop 0
	global_load_dwordx4 v[60:63], v[60:61], off offset:3072
	v_add_u32_e32 v103, v178, v98
	s_waitcnt vmcnt(15)
	ds_write_b128 v103, v[64:67]
	s_waitcnt vmcnt(14)
	ds_write_b128 v103, v[68:71] offset:1152
	v_add_u32_e32 v191, v179, v96
	ds_read_b128 v[64:67], v191
	ds_read_b128 v[68:71], v191 offset:64
	s_waitcnt lgkmcnt(1)
	v_mfma_f32_16x16x32_bf16 v[196:199], v[0:3], v[64:67], 0
	v_mfma_f32_16x16x32_bf16 v[200:203], v[8:11], v[64:67], 0
	s_waitcnt lgkmcnt(0)
	v_mfma_f32_16x16x32_bf16 v[196:199], v[4:7], v[68:71], v[196:199]
	v_mfma_f32_16x16x32_bf16 v[200:203], v[12:15], v[68:71], v[200:203]
	v_mfma_f32_16x16x32_bf16 v[204:207], v[16:19], v[64:67], 0
	s_nop 5
	v_max_f32_e32 v192, 0, v196
	v_fma_f32 v192, v162, v192, 0
	v_max_f32_e32 v195, 0, v197
	v_max_f32_e32 v193, 0, v200
	v_fmac_f32_e32 v192, v163, v195
	v_fma_f32 v193, v166, v193, 0
	v_max_f32_e32 v195, 0, v201
	v_mfma_f32_16x16x32_bf16 v[64:67], v[24:27], v[64:67], 0
	v_fmac_f32_e32 v193, v167, v195
	v_max_f32_e32 v195, 0, v198
	v_fmac_f32_e32 v192, v164, v195
	v_max_f32_e32 v195, 0, v202
	v_mfma_f32_16x16x32_bf16 v[64:67], v[28:31], v[68:71], v[64:67]
	v_fmac_f32_e32 v193, v168, v195
	v_max_f32_e32 v195, 0, v199
	v_mfma_f32_16x16x32_bf16 v[196:199], v[20:23], v[68:71], v[204:207]
	v_fmac_f32_e32 v192, v165, v195
	s_nop 2
	s_nop 0
	v_max_f32_e32 v64, 0, v64
	v_fma_f32 v64, v174, v64, 0
	s_nop 0
	v_max_f32_e32 v68, 0, v196
	v_max_f32_e32 v65, 0, v65
	v_fma_f32 v68, v170, v68, 0
	v_max_f32_e32 v69, 0, v197
	v_fmac_f32_e32 v64, v175, v65
	v_fmac_f32_e32 v68, v171, v69
	v_max_f32_e32 v65, 0, v198
	v_fmac_f32_e32 v68, v172, v65
	v_max_f32_e32 v65, 0, v66
	v_fmac_f32_e32 v64, v176, v65
	v_max_f32_e32 v65, 0, v199
	v_fmac_f32_e32 v68, v173, v65
	v_max_f32_e32 v195, 0, v203
	v_max_f32_e32 v65, 0, v67
	v_fmac_f32_e32 v193, v169, v195
	v_fmac_f32_e32 v64, v177, v65
	v_add_f32_e32 v192, v192, v193
	v_add_f32_e32 v64, v68, v64
	v_add_u32_e32 v65, 0x10000, v180
	ds_write_b32 v180, v192
	ds_write_b32 v65, v64
	s_waitcnt vmcnt(13)
	ds_write_b128 v103, v[32:35]
	s_waitcnt vmcnt(12)
	ds_write_b128 v103, v[36:39] offset:1152
	ds_read_b128 v[32:35], v191
	ds_read_b128 v[36:39], v191 offset:64
	s_waitcnt lgkmcnt(1)
	v_mfma_f32_16x16x32_bf16 v[64:67], v[0:3], v[32:35], 0
	v_mfma_f32_16x16x32_bf16 v[68:71], v[8:11], v[32:35], 0
	s_waitcnt lgkmcnt(0)
	v_mfma_f32_16x16x32_bf16 v[64:67], v[4:7], v[36:39], v[64:67]
	v_mfma_f32_16x16x32_bf16 v[68:71], v[12:15], v[36:39], v[68:71]
	v_mfma_f32_16x16x32_bf16 v[196:199], v[16:19], v[32:35], 0
	s_nop 5
	v_max_f32_e32 v64, 0, v64
	v_fma_f32 v192, v162, v64, 0
	v_max_f32_e32 v64, 0, v68
	v_fma_f32 v68, v166, v64, 0
	v_max_f32_e32 v64, 0, v65
	v_fmac_f32_e32 v192, v163, v64
	v_max_f32_e32 v64, 0, v69
	v_fmac_f32_e32 v68, v167, v64
	v_max_f32_e32 v64, 0, v66
	v_fmac_f32_e32 v192, v164, v64
	v_mfma_f32_16x16x32_bf16 v[32:35], v[24:27], v[32:35], 0
	v_max_f32_e32 v64, 0, v70
	v_fmac_f32_e32 v68, v168, v64
	v_max_f32_e32 v64, 0, v67
	v_fmac_f32_e32 v192, v165, v64
	v_mfma_f32_16x16x32_bf16 v[32:35], v[28:31], v[36:39], v[32:35]
	v_max_f32_e32 v69, 0, v71
	v_fmac_f32_e32 v68, v169, v69
	v_add_f32_e32 v68, v192, v68
	v_mfma_f32_16x16x32_bf16 v[64:67], v[20:23], v[36:39], v[196:199]
	ds_write_b32 v180, v68 offset:64
	s_nop 2
	v_max_f32_e32 v32, 0, v32
	v_fma_f32 v32, v174, v32, 0
	s_nop 1
	v_max_f32_e32 v36, 0, v64
	v_max_f32_e32 v33, 0, v33
	v_fma_f32 v36, v170, v36, 0
	v_max_f32_e32 v37, 0, v65
	v_fmac_f32_e32 v32, v175, v33
	v_fmac_f32_e32 v36, v171, v37
	v_max_f32_e32 v33, 0, v66
	v_fmac_f32_e32 v36, v172, v33
	v_max_f32_e32 v33, 0, v34
	v_fmac_f32_e32 v32, v176, v33
	v_max_f32_e32 v33, 0, v67
	v_fmac_f32_e32 v36, v173, v33
	v_max_f32_e32 v33, 0, v35
	v_fmac_f32_e32 v32, v177, v33
	v_add_f32_e32 v32, v36, v32
	v_add_u32_e32 v33, 0x10040, v180
	ds_write_b32 v33, v32
	s_add_i32 s9, s8, -2
	s_min_i32 s57, s9, s7
	v_lshl_add_u32 v32, s57, 8, v102
	v_ashrrev_i32_e32 v33, 31, v32
	v_lshlrev_b64 v[32:33], 7, v[32:33]
	v_lshl_add_u64 v[36:37], v[100:101], 0, v[32:33]
	global_load_dwordx4 v[64:67], v[36:37], off
	global_load_dwordx4 v[68:71], v[36:37], off offset:1024
	global_load_dwordx4 v[32:35], v[36:37], off offset:2048
	s_nop 0
	global_load_dwordx4 v[36:39], v[36:37], off offset:3072
	s_add_i32 s57, s8, -5
	s_cmp_ge_i32 s57, s6
	s_cbranch_scc1 .LBB0_836
	s_waitcnt vmcnt(15)
	ds_write_b128 v103, v[72:75]
	s_waitcnt vmcnt(14)
	ds_write_b128 v103, v[76:79] offset:1152
	ds_read_b128 v[72:75], v191
	ds_read_b128 v[76:79], v191 offset:64
	s_waitcnt lgkmcnt(1)
	v_mfma_f32_16x16x32_bf16 v[196:199], v[0:3], v[72:75], 0
	v_mfma_f32_16x16x32_bf16 v[200:203], v[8:11], v[72:75], 0
	s_waitcnt lgkmcnt(0)
	v_mfma_f32_16x16x32_bf16 v[196:199], v[4:7], v[76:79], v[196:199]
	v_mfma_f32_16x16x32_bf16 v[200:203], v[12:15], v[76:79], v[200:203]
	v_mfma_f32_16x16x32_bf16 v[204:207], v[16:19], v[72:75], 0
	s_nop 5
	v_max_f32_e32 v192, 0, v196
	v_fma_f32 v192, v162, v192, 0
	v_max_f32_e32 v195, 0, v197
	v_max_f32_e32 v193, 0, v200
	v_fmac_f32_e32 v192, v163, v195
	v_fma_f32 v193, v166, v193, 0
	v_max_f32_e32 v195, 0, v201
	v_mfma_f32_16x16x32_bf16 v[72:75], v[24:27], v[72:75], 0
	v_fmac_f32_e32 v193, v167, v195
	v_max_f32_e32 v195, 0, v198
	v_fmac_f32_e32 v192, v164, v195
	v_max_f32_e32 v195, 0, v202
	v_mfma_f32_16x16x32_bf16 v[72:75], v[28:31], v[76:79], v[72:75]
	v_fmac_f32_e32 v193, v168, v195
	v_max_f32_e32 v195, 0, v199
	v_mfma_f32_16x16x32_bf16 v[196:199], v[20:23], v[76:79], v[204:207]
	v_fmac_f32_e32 v192, v165, v195
	s_nop 2
	s_nop 0
	v_max_f32_e32 v72, 0, v72
	v_fma_f32 v72, v174, v72, 0
	s_nop 0
	v_max_f32_e32 v76, 0, v196
	v_max_f32_e32 v73, 0, v73
	v_fma_f32 v76, v170, v76, 0
	v_max_f32_e32 v77, 0, v197
	v_fmac_f32_e32 v72, v175, v73
	v_fmac_f32_e32 v76, v171, v77
	v_max_f32_e32 v73, 0, v198
	v_fmac_f32_e32 v76, v172, v73
	v_max_f32_e32 v73, 0, v74
	v_fmac_f32_e32 v72, v176, v73
	v_max_f32_e32 v73, 0, v199
	v_fmac_f32_e32 v76, v173, v73
	v_max_f32_e32 v195, 0, v203
	v_max_f32_e32 v73, 0, v75
	v_fmac_f32_e32 v193, v169, v195
	v_fmac_f32_e32 v72, v177, v73
	v_add_f32_e32 v192, v192, v193
	v_add_f32_e32 v72, v76, v72
	v_add_u32_e32 v73, 0x10400, v180
	ds_write_b32 v180, v192 offset:1024
	ds_write_b32 v73, v72
	s_waitcnt vmcnt(13)
	ds_write_b128 v103, v[40:43]
	s_waitcnt vmcnt(12)
	ds_write_b128 v103, v[44:47] offset:1152
	ds_read_b128 v[40:43], v191
	ds_read_b128 v[44:47], v191 offset:64
	s_waitcnt lgkmcnt(1)
	v_mfma_f32_16x16x32_bf16 v[72:75], v[0:3], v[40:43], 0
	v_mfma_f32_16x16x32_bf16 v[76:79], v[8:11], v[40:43], 0
	s_waitcnt lgkmcnt(0)
	v_mfma_f32_16x16x32_bf16 v[72:75], v[4:7], v[44:47], v[72:75]
	v_mfma_f32_16x16x32_bf16 v[76:79], v[12:15], v[44:47], v[76:79]
	v_mfma_f32_16x16x32_bf16 v[196:199], v[16:19], v[40:43], 0
	s_nop 5
	v_max_f32_e32 v72, 0, v72
	v_fma_f32 v192, v162, v72, 0
	v_max_f32_e32 v72, 0, v76
	v_fma_f32 v76, v166, v72, 0
	v_max_f32_e32 v72, 0, v73
	v_fmac_f32_e32 v192, v163, v72
	v_max_f32_e32 v72, 0, v77
	v_fmac_f32_e32 v76, v167, v72
	v_max_f32_e32 v72, 0, v74
	v_fmac_f32_e32 v192, v164, v72
	v_mfma_f32_16x16x32_bf16 v[40:43], v[24:27], v[40:43], 0
	v_max_f32_e32 v72, 0, v78
	v_fmac_f32_e32 v76, v168, v72
	v_max_f32_e32 v72, 0, v75
	v_fmac_f32_e32 v192, v165, v72
	v_mfma_f32_16x16x32_bf16 v[40:43], v[28:31], v[44:47], v[40:43]
	v_max_f32_e32 v77, 0, v79
	v_fmac_f32_e32 v76, v169, v77
	v_add_f32_e32 v76, v192, v76
	v_mfma_f32_16x16x32_bf16 v[72:75], v[20:23], v[44:47], v[196:199]
	ds_write_b32 v180, v76 offset:1088
	s_nop 2
	v_max_f32_e32 v40, 0, v40
	v_fma_f32 v40, v174, v40, 0
	s_nop 1
	v_max_f32_e32 v44, 0, v72
	v_max_f32_e32 v41, 0, v41
	v_fma_f32 v44, v170, v44, 0
	v_max_f32_e32 v45, 0, v73
	v_fmac_f32_e32 v40, v175, v41
	v_fmac_f32_e32 v44, v171, v45
	v_max_f32_e32 v41, 0, v74
	v_fmac_f32_e32 v44, v172, v41
	v_max_f32_e32 v41, 0, v42
	v_fmac_f32_e32 v40, v176, v41
	v_max_f32_e32 v41, 0, v75
	v_fmac_f32_e32 v44, v173, v41
	v_max_f32_e32 v41, 0, v43
	v_fmac_f32_e32 v40, v177, v41
	v_add_f32_e32 v40, v44, v40
	v_add_u32_e32 v41, 0x10440, v180
	ds_write_b32 v41, v40
.LBB0_836:
	s_add_i32 s57, s8, -1
	s_min_i32 s57, s57, s7
	s_waitcnt vmcnt(13)
	v_lshl_add_u32 v40, s57, 8, v102
	v_ashrrev_i32_e32 v41, 31, v40
	v_lshlrev_b64 v[40:41], 7, v[40:41]
	s_waitcnt vmcnt(12)
	v_lshl_add_u64 v[44:45], v[100:101], 0, v[40:41]
	global_load_dwordx4 v[72:75], v[44:45], off
	global_load_dwordx4 v[76:79], v[44:45], off offset:1024
	global_load_dwordx4 v[40:43], v[44:45], off offset:2048
	s_nop 0
	global_load_dwordx4 v[44:47], v[44:45], off offset:3072
	s_add_i32 s57, s8, -4
	s_cmp_ge_i32 s57, s6
	s_cbranch_scc1 .LBB0_838
	s_waitcnt vmcnt(15)
	ds_write_b128 v103, v[80:83]
	s_waitcnt vmcnt(14)
	ds_write_b128 v103, v[84:87] offset:1152
	ds_read_b128 v[80:83], v191
	ds_read_b128 v[84:87], v191 offset:64
	s_waitcnt lgkmcnt(1)
	v_mfma_f32_16x16x32_bf16 v[196:199], v[0:3], v[80:83], 0
	v_mfma_f32_16x16x32_bf16 v[200:203], v[8:11], v[80:83], 0
	s_waitcnt lgkmcnt(0)
	v_mfma_f32_16x16x32_bf16 v[196:199], v[4:7], v[84:87], v[196:199]
	v_mfma_f32_16x16x32_bf16 v[200:203], v[12:15], v[84:87], v[200:203]
	v_mfma_f32_16x16x32_bf16 v[204:207], v[16:19], v[80:83], 0
	s_nop 5
	v_max_f32_e32 v192, 0, v196
	v_fma_f32 v192, v162, v192, 0
	v_max_f32_e32 v195, 0, v197
	v_max_f32_e32 v193, 0, v200
	v_fmac_f32_e32 v192, v163, v195
	v_fma_f32 v193, v166, v193, 0
	v_max_f32_e32 v195, 0, v201
	v_mfma_f32_16x16x32_bf16 v[80:83], v[24:27], v[80:83], 0
	v_fmac_f32_e32 v193, v167, v195
	v_max_f32_e32 v195, 0, v198
	v_fmac_f32_e32 v192, v164, v195
	v_max_f32_e32 v195, 0, v202
	v_mfma_f32_16x16x32_bf16 v[80:83], v[28:31], v[84:87], v[80:83]
	v_fmac_f32_e32 v193, v168, v195
	v_max_f32_e32 v195, 0, v199
	v_mfma_f32_16x16x32_bf16 v[196:199], v[20:23], v[84:87], v[204:207]
	v_fmac_f32_e32 v192, v165, v195
	s_nop 2
	s_nop 0
	v_max_f32_e32 v80, 0, v80
	v_fma_f32 v80, v174, v80, 0
	s_nop 0
	v_max_f32_e32 v84, 0, v196
	v_max_f32_e32 v81, 0, v81
	v_fma_f32 v84, v170, v84, 0
	v_max_f32_e32 v85, 0, v197
	v_fmac_f32_e32 v80, v175, v81
	v_fmac_f32_e32 v84, v171, v85
	v_max_f32_e32 v81, 0, v198
	v_fmac_f32_e32 v84, v172, v81
	v_max_f32_e32 v81, 0, v82
	v_fmac_f32_e32 v80, v176, v81
	v_max_f32_e32 v81, 0, v199
	v_fmac_f32_e32 v84, v173, v81
	v_max_f32_e32 v195, 0, v203
	v_max_f32_e32 v81, 0, v83
	v_fmac_f32_e32 v193, v169, v195
	v_fmac_f32_e32 v80, v177, v81
	v_add_f32_e32 v192, v192, v193
	v_add_f32_e32 v80, v84, v80
	v_add_u32_e32 v81, 0x10800, v180
	ds_write_b32 v180, v192 offset:2048
	ds_write_b32 v81, v80
	s_waitcnt vmcnt(13)
	ds_write_b128 v103, v[48:51]
	s_waitcnt vmcnt(12)
	ds_write_b128 v103, v[52:55] offset:1152
	ds_read_b128 v[48:51], v191
	ds_read_b128 v[52:55], v191 offset:64
	s_waitcnt lgkmcnt(1)
	v_mfma_f32_16x16x32_bf16 v[80:83], v[0:3], v[48:51], 0
	v_mfma_f32_16x16x32_bf16 v[84:87], v[8:11], v[48:51], 0
	s_waitcnt lgkmcnt(0)
	v_mfma_f32_16x16x32_bf16 v[80:83], v[4:7], v[52:55], v[80:83]
	v_mfma_f32_16x16x32_bf16 v[84:87], v[12:15], v[52:55], v[84:87]
	v_mfma_f32_16x16x32_bf16 v[196:199], v[16:19], v[48:51], 0
	s_nop 5
	v_max_f32_e32 v80, 0, v80
	v_fma_f32 v192, v162, v80, 0
	v_max_f32_e32 v80, 0, v84
	v_fma_f32 v84, v166, v80, 0
	v_max_f32_e32 v80, 0, v81
	v_fmac_f32_e32 v192, v163, v80
	v_max_f32_e32 v80, 0, v85
	v_fmac_f32_e32 v84, v167, v80
	v_max_f32_e32 v80, 0, v82
	v_fmac_f32_e32 v192, v164, v80
	v_mfma_f32_16x16x32_bf16 v[48:51], v[24:27], v[48:51], 0
	v_max_f32_e32 v80, 0, v86
	v_fmac_f32_e32 v84, v168, v80
	v_max_f32_e32 v80, 0, v83
	v_fmac_f32_e32 v192, v165, v80
	v_mfma_f32_16x16x32_bf16 v[48:51], v[28:31], v[52:55], v[48:51]
	v_max_f32_e32 v85, 0, v87
	v_fmac_f32_e32 v84, v169, v85
	v_add_f32_e32 v84, v192, v84
	v_mfma_f32_16x16x32_bf16 v[80:83], v[20:23], v[52:55], v[196:199]
	ds_write_b32 v180, v84 offset:2112
	s_nop 2
	v_max_f32_e32 v48, 0, v48
	v_fma_f32 v48, v174, v48, 0
	s_nop 1
	v_max_f32_e32 v52, 0, v80
	v_max_f32_e32 v49, 0, v49
	v_fma_f32 v52, v170, v52, 0
	v_max_f32_e32 v53, 0, v81
	v_fmac_f32_e32 v48, v175, v49
	v_fmac_f32_e32 v52, v171, v53
	v_max_f32_e32 v49, 0, v82
	v_fmac_f32_e32 v52, v172, v49
	v_max_f32_e32 v49, 0, v50
	v_fmac_f32_e32 v48, v176, v49
	v_max_f32_e32 v49, 0, v83
	v_fmac_f32_e32 v52, v173, v49
	v_max_f32_e32 v49, 0, v51
	v_fmac_f32_e32 v48, v177, v49
	v_add_f32_e32 v48, v52, v48
	v_add_u32_e32 v49, 0x10840, v180
	ds_write_b32 v49, v48
.LBB0_838:
	s_min_i32 s57, s8, s7
	s_cmp_ge_i32 s40, s6
	s_waitcnt vmcnt(13)
	v_lshl_add_u32 v48, s57, 8, v102
	v_ashrrev_i32_e32 v49, 31, v48
	v_lshlrev_b64 v[48:49], 7, v[48:49]
	s_waitcnt vmcnt(12)
	v_lshl_add_u64 v[52:53], v[100:101], 0, v[48:49]
	global_load_dwordx4 v[80:83], v[52:53], off
	global_load_dwordx4 v[84:87], v[52:53], off offset:1024
	global_load_dwordx4 v[48:51], v[52:53], off offset:2048
	s_nop 0
	global_load_dwordx4 v[52:55], v[52:53], off offset:3072
	s_cbranch_scc1 .LBB0_833
	s_waitcnt vmcnt(15)
	ds_write_b128 v103, v[88:91]
	s_waitcnt vmcnt(14)
	ds_write_b128 v103, v[92:95] offset:1152
	ds_read_b128 v[88:91], v191
	ds_read_b128 v[92:95], v191 offset:64
	s_waitcnt lgkmcnt(1)
	v_mfma_f32_16x16x32_bf16 v[196:199], v[0:3], v[88:91], 0
	v_mfma_f32_16x16x32_bf16 v[200:203], v[8:11], v[88:91], 0
	s_waitcnt lgkmcnt(0)
	v_mfma_f32_16x16x32_bf16 v[196:199], v[4:7], v[92:95], v[196:199]
	v_mfma_f32_16x16x32_bf16 v[200:203], v[12:15], v[92:95], v[200:203]
	v_mfma_f32_16x16x32_bf16 v[204:207], v[16:19], v[88:91], 0
	s_nop 5
	v_max_f32_e32 v192, 0, v196
	v_fma_f32 v192, v162, v192, 0
	v_max_f32_e32 v195, 0, v197
	v_max_f32_e32 v193, 0, v200
	v_fmac_f32_e32 v192, v163, v195
	v_fma_f32 v193, v166, v193, 0
	v_max_f32_e32 v195, 0, v201
	v_mfma_f32_16x16x32_bf16 v[88:91], v[24:27], v[88:91], 0
	v_fmac_f32_e32 v193, v167, v195
	v_max_f32_e32 v195, 0, v198
	v_fmac_f32_e32 v192, v164, v195
	v_max_f32_e32 v195, 0, v202
	v_mfma_f32_16x16x32_bf16 v[88:91], v[28:31], v[92:95], v[88:91]
	v_fmac_f32_e32 v193, v168, v195
	v_max_f32_e32 v195, 0, v199
	v_mfma_f32_16x16x32_bf16 v[196:199], v[20:23], v[92:95], v[204:207]
	v_fmac_f32_e32 v192, v165, v195
	s_nop 2
	s_nop 0
	v_max_f32_e32 v88, 0, v88
	v_fma_f32 v88, v174, v88, 0
	s_nop 0
	v_max_f32_e32 v92, 0, v196
	v_max_f32_e32 v89, 0, v89
	v_fma_f32 v92, v170, v92, 0
	v_max_f32_e32 v93, 0, v197
	v_fmac_f32_e32 v88, v175, v89
	v_fmac_f32_e32 v92, v171, v93
	v_max_f32_e32 v89, 0, v198
	v_fmac_f32_e32 v92, v172, v89
	v_max_f32_e32 v89, 0, v90
	v_fmac_f32_e32 v88, v176, v89
	v_max_f32_e32 v89, 0, v199
	v_fmac_f32_e32 v92, v173, v89
	v_max_f32_e32 v195, 0, v203
	v_max_f32_e32 v89, 0, v91
	v_fmac_f32_e32 v193, v169, v195
	v_fmac_f32_e32 v88, v177, v89
	v_add_f32_e32 v192, v192, v193
	v_add_f32_e32 v88, v92, v88
	v_add_u32_e32 v89, 0x10c00, v180
	ds_write_b32 v180, v192 offset:3072
	ds_write_b32 v89, v88
	s_waitcnt vmcnt(13)
	ds_write_b128 v103, v[56:59]
	s_waitcnt vmcnt(12)
	ds_write_b128 v103, v[60:63] offset:1152
	ds_read_b128 v[56:59], v191
	ds_read_b128 v[60:63], v191 offset:64
	s_waitcnt lgkmcnt(1)
	v_mfma_f32_16x16x32_bf16 v[88:91], v[0:3], v[56:59], 0
	v_mfma_f32_16x16x32_bf16 v[92:95], v[8:11], v[56:59], 0
	s_waitcnt lgkmcnt(0)
	v_mfma_f32_16x16x32_bf16 v[88:91], v[4:7], v[60:63], v[88:91]
	v_mfma_f32_16x16x32_bf16 v[92:95], v[12:15], v[60:63], v[92:95]
	v_mfma_f32_16x16x32_bf16 v[196:199], v[16:19], v[56:59], 0
	s_nop 5
	v_max_f32_e32 v88, 0, v88
	v_fma_f32 v103, v162, v88, 0
	v_max_f32_e32 v88, 0, v92
	v_fma_f32 v92, v166, v88, 0
	v_max_f32_e32 v88, 0, v89
	v_fmac_f32_e32 v103, v163, v88
	v_max_f32_e32 v88, 0, v93
	v_fmac_f32_e32 v92, v167, v88
	v_max_f32_e32 v88, 0, v90
	v_fmac_f32_e32 v103, v164, v88
	v_mfma_f32_16x16x32_bf16 v[56:59], v[24:27], v[56:59], 0
	v_max_f32_e32 v88, 0, v94
	v_fmac_f32_e32 v92, v168, v88
	v_max_f32_e32 v88, 0, v91
	v_fmac_f32_e32 v103, v165, v88
	v_mfma_f32_16x16x32_bf16 v[56:59], v[28:31], v[60:63], v[56:59]
	v_max_f32_e32 v93, 0, v95
	v_fmac_f32_e32 v92, v169, v93
	v_add_f32_e32 v92, v103, v92
	v_mfma_f32_16x16x32_bf16 v[88:91], v[20:23], v[60:63], v[196:199]
	ds_write_b32 v180, v92 offset:3136
	s_nop 2
	v_max_f32_e32 v56, 0, v56
	v_fma_f32 v56, v174, v56, 0
	s_nop 1
	v_max_f32_e32 v60, 0, v88
	v_max_f32_e32 v57, 0, v57
	v_fma_f32 v60, v170, v60, 0
	v_max_f32_e32 v61, 0, v89
	v_fmac_f32_e32 v56, v175, v57
	v_fmac_f32_e32 v60, v171, v61
	v_max_f32_e32 v57, 0, v90
	v_fmac_f32_e32 v60, v172, v57
	v_max_f32_e32 v57, 0, v58
	v_fmac_f32_e32 v56, v176, v57
	v_max_f32_e32 v57, 0, v91
	v_fmac_f32_e32 v60, v173, v57
	v_max_f32_e32 v57, 0, v59
	v_fmac_f32_e32 v56, v177, v57
	v_add_f32_e32 v56, v60, v56
	v_add_u32_e32 v57, 0x10c40, v180
	ds_write_b32 v57, v56
	s_branch .LBB0_833

.LBB0_1264:
	s_or_b64 exec, exec, s[8:9]
	v_lshrrev_b32_e32 v122, 3, v117
	v_lshl_add_u32 v119, v122, 2, s47
	s_waitcnt lgkmcnt(0)
	ds_read2_b32 v[4:5], v119 offset1:8
	ds_read2_b32 v[12:13], v119 offset0:16 offset1:24
	v_lshlrev_b32_e32 v6, 4, v120
	s_add_u32 s8, s20, s42
	v_and_b32_e32 v118, 0x70, v6
	s_waitcnt lgkmcnt(1)
	v_lshlrev_b32_e32 v4, 9, v4
	v_lshlrev_b32_e32 v5, 9, v5
	s_waitcnt lgkmcnt(0)
	v_lshlrev_b32_e32 v12, 9, v12
	v_lshlrev_b32_e32 v13, 9, v13
	s_addc_u32 s9, s21, 0
	v_and_or_b32 v4, v4, s43, v118
	v_and_or_b32 v8, v5, s43, v118
	v_and_or_b32 v12, v12, s43, v118
	v_and_or_b32 v16, v13, s43, v118
	global_load_dwordx4 v[4:7], v4, s[8:9]
	s_nop 0
	global_load_dwordx4 v[8:11], v8, s[8:9]
	ds_read2_b32 v[20:21], v119 offset0:32 offset1:40
	global_load_dwordx4 v[12:15], v12, s[8:9]
	s_nop 0
	global_load_dwordx4 v[16:19], v16, s[8:9]
	ds_read2_b32 v[28:29], v119 offset0:48 offset1:56
	s_add_u32 s18, s18, s42
	s_addc_u32 s19, s19, 0
	s_waitcnt lgkmcnt(1)
	v_lshlrev_b32_e32 v20, 9, v20
	v_lshlrev_b32_e32 v21, 9, v21
	s_waitcnt lgkmcnt(0)
	v_lshlrev_b32_e32 v28, 9, v28
	v_lshlrev_b32_e32 v29, 9, v29
	v_and_or_b32 v20, v20, s43, v118
	v_and_or_b32 v24, v21, s43, v118
	v_and_or_b32 v28, v28, s43, v118
	v_and_or_b32 v32, v29, s43, v118
	global_load_dwordx4 v[20:23], v20, s[8:9]
	s_nop 0
	global_load_dwordx4 v[24:27], v24, s[8:9]
	ds_read2_b32 v[36:37], v119 offset0:64 offset1:72
	global_load_dwordx4 v[28:31], v28, s[8:9]
	s_nop 0
	global_load_dwordx4 v[32:35], v32, s[8:9]
	ds_read2_b32 v[44:45], v119 offset0:80 offset1:88
	s_waitcnt lgkmcnt(1)
	v_lshlrev_b32_e32 v36, 9, v36
	v_lshlrev_b32_e32 v37, 9, v37
	s_waitcnt lgkmcnt(0)
	v_lshlrev_b32_e32 v44, 9, v44
	v_lshlrev_b32_e32 v45, 9, v45
	v_and_or_b32 v36, v36, s43, v118
	v_and_or_b32 v40, v37, s43, v118
	v_and_or_b32 v44, v44, s43, v118
	v_and_or_b32 v48, v45, s43, v118
	global_load_dwordx4 v[36:39], v36, s[8:9]
	s_nop 0
	global_load_dwordx4 v[40:43], v40, s[8:9]
	s_nop 0
	global_load_dwordx4 v[44:47], v44, s[8:9]
	s_nop 0
	global_load_dwordx4 v[48:51], v48, s[8:9]
	ds_read2_b32 v[52:53], v119 offset0:96 offset1:104
	ds_read2_b32 v[64:65], v119 offset0:112 offset1:120
	v_add_u32_e32 v112, s47, v112
	v_add_u32_e32 v121, s47, v118
	v_mad_u32_u24 v123, v116, s44, v112
	s_waitcnt lgkmcnt(1)
	v_lshlrev_b32_e32 v52, 9, v52
	v_lshlrev_b32_e32 v53, 9, v53
	s_waitcnt lgkmcnt(0)
	v_lshlrev_b32_e32 v64, 9, v64
	v_lshlrev_b32_e32 v65, 9, v65
	v_and_or_b32 v52, v52, s43, v118
	v_and_or_b32 v60, v53, s43, v118
	v_and_or_b32 v64, v64, s43, v118
	v_and_or_b32 v68, v65, s43, v118
	global_load_dwordx4 v[52:55], v52, s[8:9]
	s_nop 0
	global_load_dwordx4 v[60:63], v60, s[8:9]
	s_nop 0
	global_load_dwordx4 v[64:67], v64, s[8:9]
	s_nop 0
	global_load_dwordx4 v[68:71], v68, s[8:9]
	v_mad_u32_u24 v132, v122, s44, v121
	s_waitcnt vmcnt(15)
	ds_write_b128 v132, v[4:7] offset:1024
	s_waitcnt vmcnt(14)
	ds_write_b128 v132, v[8:11] offset:2304
	s_waitcnt vmcnt(13)
	ds_write_b128 v132, v[12:15] offset:3584
	s_waitcnt vmcnt(12)
	ds_write_b128 v132, v[16:19] offset:4864
	ds_read_b128 v[4:7], v123 offset:1024
	ds_read_b128 v[8:11], v123 offset:1088
	ds_read_b128 v[12:15], v123 offset:3584
	ds_read_b128 v[16:19], v123 offset:3648
	ds_read2_b32 v[72:73], v119 offset0:128 offset1:136
	ds_read2_b32 v[74:75], v119 offset0:144 offset1:152
	s_waitcnt lgkmcnt(5)
	v_mfma_f32_16x16x32_bf16 v[4:7], v[4:7], v[0:3], 0
	s_waitcnt lgkmcnt(1)
	v_lshlrev_b32_e32 v72, 9, v72
	v_mfma_f32_16x16x32_bf16 v[108:111], v[8:11], v[56:59], v[4:7]
	v_mfma_f32_16x16x32_bf16 v[12:15], v[12:15], v[0:3], 0
	s_nop 3
	v_and_or_b32 v4, v72, s43, v118
	v_lshlrev_b32_e32 v5, 9, v73
	s_waitcnt lgkmcnt(0)
	v_lshlrev_b32_e32 v72, 9, v74
	v_lshlrev_b32_e32 v73, 9, v75
	v_and_or_b32 v8, v5, s43, v118
	v_and_or_b32 v72, v72, s43, v118
	v_and_or_b32 v76, v73, s43, v118
	global_load_dwordx4 v[4:7], v4, s[8:9]
	s_nop 0
	global_load_dwordx4 v[8:11], v8, s[8:9]
	s_nop 0
	global_load_dwordx4 v[72:75], v72, s[8:9]
	s_nop 0
	global_load_dwordx4 v[76:79], v76, s[8:9]
	v_mfma_f32_16x16x32_bf16 v[104:107], v[16:19], v[56:59], v[12:15]
	s_waitcnt vmcnt(15)
	ds_write_b128 v132, v[20:23] offset:1024
	s_waitcnt vmcnt(14)
	ds_write_b128 v132, v[24:27] offset:2304
	s_waitcnt vmcnt(13)
	ds_write_b128 v132, v[28:31] offset:3584
	s_waitcnt vmcnt(12)
	ds_write_b128 v132, v[32:35] offset:4864
	ds_read_b128 v[12:15], v123 offset:1024
	ds_read_b128 v[16:19], v123 offset:1088
	ds_read_b128 v[20:23], v123 offset:3584
	ds_read_b128 v[24:27], v123 offset:3648
	ds_read2_b32 v[28:29], v119 offset0:160 offset1:168
	ds_read2_b32 v[30:31], v119 offset0:176 offset1:184
	s_waitcnt lgkmcnt(5)
	v_mfma_f32_16x16x32_bf16 v[12:15], v[12:15], v[0:3], 0
	s_waitcnt lgkmcnt(1)
	v_lshlrev_b32_e32 v28, 9, v28
	v_mfma_f32_16x16x32_bf16 v[100:103], v[16:19], v[56:59], v[12:15]
	v_mfma_f32_16x16x32_bf16 v[20:23], v[20:23], v[0:3], 0
	s_nop 3
	v_and_or_b32 v12, v28, s43, v118
	v_lshlrev_b32_e32 v13, 9, v29
	s_waitcnt lgkmcnt(0)
	v_lshlrev_b32_e32 v28, 9, v30
	v_lshlrev_b32_e32 v29, 9, v31
	v_and_or_b32 v16, v13, s43, v118
	v_and_or_b32 v28, v28, s43, v118
	v_and_or_b32 v32, v29, s43, v118
	global_load_dwordx4 v[12:15], v12, s[8:9]
	s_nop 0
	global_load_dwordx4 v[16:19], v16, s[8:9]
	s_nop 0
	global_load_dwordx4 v[28:31], v28, s[8:9]
	s_nop 0
	global_load_dwordx4 v[32:35], v32, s[8:9]
	v_mfma_f32_16x16x32_bf16 v[96:99], v[24:27], v[56:59], v[20:23]
	s_waitcnt vmcnt(15)
	ds_write_b128 v132, v[36:39] offset:1024
	s_waitcnt vmcnt(14)
	ds_write_b128 v132, v[40:43] offset:2304
	s_waitcnt vmcnt(13)
	ds_write_b128 v132, v[44:47] offset:3584
	s_waitcnt vmcnt(12)
	ds_write_b128 v132, v[48:51] offset:4864
	ds_read_b128 v[20:23], v123 offset:1024
	ds_read_b128 v[24:27], v123 offset:1088
	ds_read_b128 v[36:39], v123 offset:3584
	ds_read_b128 v[40:43], v123 offset:3648
	ds_read2_b32 v[44:45], v119 offset0:192 offset1:200
	ds_read2_b32 v[46:47], v119 offset0:208 offset1:216
	s_waitcnt lgkmcnt(5)
	v_mfma_f32_16x16x32_bf16 v[20:23], v[20:23], v[0:3], 0
	s_waitcnt lgkmcnt(1)
	v_lshlrev_b32_e32 v44, 9, v44
	v_mfma_f32_16x16x32_bf16 v[92:95], v[24:27], v[56:59], v[20:23]
	v_mfma_f32_16x16x32_bf16 v[36:39], v[36:39], v[0:3], 0
	s_nop 3
	v_and_or_b32 v20, v44, s43, v118
	v_lshlrev_b32_e32 v21, 9, v45
	s_waitcnt lgkmcnt(0)
	v_lshlrev_b32_e32 v44, 9, v46
	v_lshlrev_b32_e32 v45, 9, v47
	v_and_or_b32 v24, v21, s43, v118
	v_and_or_b32 v44, v44, s43, v118
	v_and_or_b32 v48, v45, s43, v118
	global_load_dwordx4 v[20:23], v20, s[8:9]
	s_nop 0
	global_load_dwordx4 v[24:27], v24, s[8:9]
	s_nop 0
	global_load_dwordx4 v[44:47], v44, s[8:9]
	s_nop 0
	global_load_dwordx4 v[48:51], v48, s[8:9]
	v_mfma_f32_16x16x32_bf16 v[88:91], v[40:43], v[56:59], v[36:39]
	s_waitcnt vmcnt(15)
	ds_write_b128 v132, v[52:55] offset:1024
	s_waitcnt vmcnt(14)
	ds_write_b128 v132, v[60:63] offset:2304
	s_waitcnt vmcnt(13)
	ds_write_b128 v132, v[64:67] offset:3584
	s_waitcnt vmcnt(12)
	ds_write_b128 v132, v[68:71] offset:4864
	ds_read_b128 v[36:39], v123 offset:1024
	ds_read_b128 v[40:43], v123 offset:1088
	ds_read_b128 v[52:55], v123 offset:3584
	ds_read_b128 v[60:63], v123 offset:3648
	ds_read2_b32 v[64:65], v119 offset0:224 offset1:232
	ds_read2_b32 v[66:67], v119 offset0:240 offset1:248
	s_waitcnt lgkmcnt(5)
	v_mfma_f32_16x16x32_bf16 v[36:39], v[36:39], v[0:3], 0
	s_waitcnt lgkmcnt(1)
	v_lshlrev_b32_e32 v64, 9, v64
	v_mfma_f32_16x16x32_bf16 v[84:87], v[40:43], v[56:59], v[36:39]
	v_mfma_f32_16x16x32_bf16 v[52:55], v[52:55], v[0:3], 0
	s_nop 3
	v_and_or_b32 v36, v64, s43, v118
	v_lshlrev_b32_e32 v37, 9, v65
	s_waitcnt lgkmcnt(0)
	v_lshlrev_b32_e32 v64, 9, v66
	v_and_or_b32 v40, v37, s43, v118
	v_and_or_b32 v64, v64, s43, v118
	v_lshlrev_b32_e32 v65, 9, v67
	global_load_dwordx4 v[36:39], v36, s[8:9]
	s_nop 0
	global_load_dwordx4 v[40:43], v40, s[8:9]
	v_and_or_b32 v65, v65, s43, v118
	global_load_dwordx4 v[124:127], v64, s[8:9]
	global_load_dwordx4 v[128:131], v65, s[8:9]
	v_mfma_f32_16x16x32_bf16 v[80:83], v[60:63], v[56:59], v[52:55]
	s_waitcnt vmcnt(15)
	ds_write_b128 v132, v[4:7] offset:1024
	s_waitcnt vmcnt(14)
	ds_write_b128 v132, v[8:11] offset:2304
	s_waitcnt vmcnt(13)
	ds_write_b128 v132, v[72:75] offset:3584
	s_waitcnt vmcnt(12)
	ds_write_b128 v132, v[76:79] offset:4864
	ds_read_b128 v[4:7], v123 offset:1024
	ds_read_b128 v[8:11], v123 offset:1088
	ds_read_b128 v[52:55], v123 offset:3584
	ds_read_b128 v[60:63], v123 offset:3648
	s_waitcnt lgkmcnt(3)
	v_mfma_f32_16x16x32_bf16 v[4:7], v[4:7], v[0:3], 0
	s_waitcnt lgkmcnt(1)
	v_mfma_f32_16x16x32_bf16 v[52:55], v[52:55], v[0:3], 0
	v_mfma_f32_16x16x32_bf16 v[76:79], v[8:11], v[56:59], v[4:7]
	s_waitcnt lgkmcnt(0)
	v_mfma_f32_16x16x32_bf16 v[72:75], v[60:63], v[56:59], v[52:55]
	s_waitcnt vmcnt(11)
	ds_write_b128 v132, v[12:15] offset:1024
	s_waitcnt vmcnt(10)
	ds_write_b128 v132, v[16:19] offset:2304
	s_waitcnt vmcnt(9)
	ds_write_b128 v132, v[28:31] offset:3584
	s_waitcnt vmcnt(8)
	ds_write_b128 v132, v[32:35] offset:4864
	ds_read_b128 v[4:7], v123 offset:1024
	ds_read_b128 v[8:11], v123 offset:1088
	ds_read_b128 v[12:15], v123 offset:3584
	ds_read_b128 v[16:19], v123 offset:3648
	s_waitcnt lgkmcnt(3)
	v_mfma_f32_16x16x32_bf16 v[4:7], v[4:7], v[0:3], 0
	s_waitcnt lgkmcnt(1)
	v_mfma_f32_16x16x32_bf16 v[12:15], v[12:15], v[0:3], 0
	v_mfma_f32_16x16x32_bf16 v[68:71], v[8:11], v[56:59], v[4:7]
	s_waitcnt lgkmcnt(0)
	v_mfma_f32_16x16x32_bf16 v[64:67], v[16:19], v[56:59], v[12:15]
	s_waitcnt vmcnt(7)
	ds_write_b128 v132, v[20:23] offset:1024
	s_waitcnt vmcnt(6)
	ds_write_b128 v132, v[24:27] offset:2304
	s_waitcnt vmcnt(5)
	ds_write_b128 v132, v[44:47] offset:3584
	s_waitcnt vmcnt(4)
	ds_write_b128 v132, v[48:51] offset:4864
	ds_read_b128 v[4:7], v123 offset:1024
	ds_read_b128 v[8:11], v123 offset:1088
	ds_read_b128 v[12:15], v123 offset:3584
	ds_read_b128 v[16:19], v123 offset:3648
	s_waitcnt lgkmcnt(3)
	v_mfma_f32_16x16x32_bf16 v[4:7], v[4:7], v[0:3], 0
	s_waitcnt lgkmcnt(1)
	v_mfma_f32_16x16x32_bf16 v[12:15], v[12:15], v[0:3], 0
	v_mfma_f32_16x16x32_bf16 v[60:63], v[8:11], v[56:59], v[4:7]
	s_waitcnt lgkmcnt(0)
	v_mfma_f32_16x16x32_bf16 v[52:55], v[16:19], v[56:59], v[12:15]
	s_waitcnt vmcnt(3)
	ds_write_b128 v132, v[36:39] offset:1024
	s_waitcnt vmcnt(2)
	ds_write_b128 v132, v[40:43] offset:2304
	s_waitcnt vmcnt(1)
	ds_write_b128 v132, v[124:127] offset:3584
	s_waitcnt vmcnt(0)
	ds_write_b128 v132, v[128:131] offset:4864
	ds_read_b128 v[4:7], v123 offset:1024
	ds_read_b128 v[8:11], v123 offset:1088
	ds_read_b128 v[12:15], v123 offset:3584
	ds_read_b128 v[124:127], v123 offset:3648
	s_waitcnt lgkmcnt(3)
	v_mfma_f32_16x16x32_bf16 v[4:7], v[4:7], v[0:3], 0
	s_waitcnt lgkmcnt(1)
	v_mfma_f32_16x16x32_bf16 v[128:131], v[12:15], v[0:3], 0
	ds_read2_b32 v[0:1], v119 offset1:8
	ds_read2_b32 v[2:3], v119 offset0:16 offset1:24
	s_waitcnt lgkmcnt(1)
	v_lshlrev_b32_e32 v0, 9, v0
	v_and_or_b32 v0, v0, s43, v118
	v_lshlrev_b32_e32 v1, 9, v1
	v_and_or_b32 v1, v1, s43, v118
	global_load_dwordx4 v[32:35], v0, s[18:19]
	global_load_dwordx4 v[36:39], v1, s[18:19]
	s_waitcnt lgkmcnt(0)
	v_lshlrev_b32_e32 v0, 9, v2
	v_and_or_b32 v2, v0, s43, v118
	ds_read2_b32 v[0:1], v119 offset0:32 offset1:40
	v_lshlrev_b32_e32 v3, 9, v3
	v_and_or_b32 v3, v3, s43, v118
	global_load_dwordx4 v[40:43], v2, s[18:19]
	global_load_dwordx4 v[44:47], v3, s[18:19]
	ds_read2_b32 v[2:3], v119 offset0:48 offset1:56
	s_waitcnt lgkmcnt(1)
	v_lshlrev_b32_e32 v0, 9, v0
	v_and_or_b32 v0, v0, s43, v118
	v_lshlrev_b32_e32 v1, 9, v1
	v_and_or_b32 v1, v1, s43, v118
	global_load_dwordx4 v[16:19], v0, s[18:19]
	global_load_dwordx4 v[20:23], v1, s[18:19]
	s_waitcnt lgkmcnt(0)
	v_lshlrev_b32_e32 v0, 9, v2
	v_and_or_b32 v2, v0, s43, v118
	v_lshlrev_b32_e32 v3, 9, v3
	v_mfma_f32_16x16x32_bf16 v[48:51], v[8:11], v[56:59], v[4:7]
	ds_read2_b32 v[0:1], v119 offset0:64 offset1:72
	v_and_or_b32 v3, v3, s43, v118
	global_load_dwordx4 v[24:27], v2, s[18:19]
	global_load_dwordx4 v[28:31], v3, s[18:19]
	ds_read2_b32 v[8:9], v119 offset0:80 offset1:88
	v_mfma_f32_16x16x32_bf16 v[56:59], v[124:127], v[56:59], v[128:131]
	s_waitcnt lgkmcnt(1)
	v_lshlrev_b32_e32 v0, 9, v0
	v_lshlrev_b32_e32 v1, 9, v1
	v_and_or_b32 v0, v0, s43, v118
	s_waitcnt lgkmcnt(0)
	v_lshlrev_b32_e32 v8, 9, v8
	v_lshlrev_b32_e32 v9, 9, v9
	v_and_or_b32 v4, v1, s43, v118
	v_and_or_b32 v8, v8, s43, v118
	v_and_or_b32 v12, v9, s43, v118
	global_load_dwordx4 v[0:3], v0, s[18:19]
	s_nop 0
	global_load_dwordx4 v[4:7], v4, s[18:19]
	s_nop 0
	global_load_dwordx4 v[8:11], v8, s[18:19]
	s_nop 0
	global_load_dwordx4 v[12:15], v12, s[18:19]
	v_and_b32_e32 v123, 12, v116
	v_add_u32_e32 v123, v112, v123
	v_and_b32_e32 v112, 3, v120
	v_lshl_add_u32 v112, v112, 2, s41
	ds_read_b32 v136, v123
	ds_read_b32 v137, v123 offset:64
	ds_read_b32 v138, v123 offset:128
	ds_read_b32 v139, v123 offset:192
	ds_read_b32 v140, v123 offset:256
	ds_read_b32 v141, v123 offset:320
	ds_read_b32 v142, v123 offset:384
	ds_read_b32 v143, v123 offset:448
	ds_read_b32 v144, v123 offset:512
	ds_read_b32 v145, v123 offset:576
	ds_read_b32 v146, v123 offset:640
	ds_read_b32 v147, v123 offset:704
	ds_read_b32 v148, v123 offset:768
	ds_read_b32 v149, v123 offset:832
	ds_read_b32 v150, v123 offset:896
	ds_read_b32 v151, v123 offset:960
	s_movk_i32 s8, 0x7c0
	v_mov_b32_e32 v168, 0xf149f2ca
	v_mov_b32_dpp v108, v109 row_shr:4 row_mask:0xf bank_mask:0x2
	v_mov_b32_dpp v104, v105 row_shr:4 row_mask:0xf bank_mask:0x2
	v_mov_b32_dpp v100, v101 row_shr:4 row_mask:0xf bank_mask:0x2
	v_mov_b32_dpp v96, v97 row_shr:4 row_mask:0xf bank_mask:0x2
	v_mov_b32_dpp v92, v93 row_shr:4 row_mask:0xf bank_mask:0x2
	v_mov_b32_dpp v88, v89 row_shr:4 row_mask:0xf bank_mask:0x2
	v_mov_b32_dpp v84, v85 row_shr:4 row_mask:0xf bank_mask:0x2
	v_mov_b32_dpp v80, v81 row_shr:4 row_mask:0xf bank_mask:0x2
	v_mov_b32_dpp v76, v77 row_shr:4 row_mask:0xf bank_mask:0x2
	v_mov_b32_dpp v72, v73 row_shr:4 row_mask:0xf bank_mask:0x2
	v_mov_b32_dpp v68, v69 row_shr:4 row_mask:0xf bank_mask:0x2
	v_mov_b32_dpp v64, v65 row_shr:4 row_mask:0xf bank_mask:0x2
	v_mov_b32_dpp v60, v61 row_shr:4 row_mask:0xf bank_mask:0x2
	v_mov_b32_dpp v52, v53 row_shr:4 row_mask:0xf bank_mask:0x2
	v_mov_b32_dpp v48, v49 row_shr:4 row_mask:0xf bank_mask:0x2
	v_mov_b32_dpp v56, v57 row_shr:4 row_mask:0xf bank_mask:0x2
	v_mov_b32_dpp v108, v110 row_shr:8 row_mask:0xf bank_mask:0x4
	v_mov_b32_dpp v104, v106 row_shr:8 row_mask:0xf bank_mask:0x4
	v_mov_b32_dpp v100, v102 row_shr:8 row_mask:0xf bank_mask:0x4
	v_mov_b32_dpp v96, v98 row_shr:8 row_mask:0xf bank_mask:0x4
	v_mov_b32_dpp v92, v94 row_shr:8 row_mask:0xf bank_mask:0x4
	v_mov_b32_dpp v88, v90 row_shr:8 row_mask:0xf bank_mask:0x4
	v_mov_b32_dpp v84, v86 row_shr:8 row_mask:0xf bank_mask:0x4
	v_mov_b32_dpp v80, v82 row_shr:8 row_mask:0xf bank_mask:0x4
	v_mov_b32_dpp v76, v78 row_shr:8 row_mask:0xf bank_mask:0x4
	v_mov_b32_dpp v72, v74 row_shr:8 row_mask:0xf bank_mask:0x4
	v_mov_b32_dpp v68, v70 row_shr:8 row_mask:0xf bank_mask:0x4
	v_mov_b32_dpp v64, v66 row_shr:8 row_mask:0xf bank_mask:0x4
	v_mov_b32_dpp v60, v62 row_shr:8 row_mask:0xf bank_mask:0x4
	v_mov_b32_dpp v52, v54 row_shr:8 row_mask:0xf bank_mask:0x4
	v_mov_b32_dpp v48, v50 row_shr:8 row_mask:0xf bank_mask:0x4
	v_mov_b32_dpp v56, v58 row_shr:8 row_mask:0xf bank_mask:0x4
	v_mov_b32_dpp v108, v111 row_shr:12 row_mask:0xf bank_mask:0x8
	v_mov_b32_dpp v104, v107 row_shr:12 row_mask:0xf bank_mask:0x8
	v_mov_b32_dpp v100, v103 row_shr:12 row_mask:0xf bank_mask:0x8
	v_mov_b32_dpp v96, v99 row_shr:12 row_mask:0xf bank_mask:0x8
	v_mov_b32_dpp v92, v95 row_shr:12 row_mask:0xf bank_mask:0x8
	v_mov_b32_dpp v88, v91 row_shr:12 row_mask:0xf bank_mask:0x8
	v_mov_b32_dpp v84, v87 row_shr:12 row_mask:0xf bank_mask:0x8
	v_mov_b32_dpp v80, v83 row_shr:12 row_mask:0xf bank_mask:0x8
	v_mov_b32_dpp v76, v79 row_shr:12 row_mask:0xf bank_mask:0x8
	v_mov_b32_dpp v72, v75 row_shr:12 row_mask:0xf bank_mask:0x8
	v_mov_b32_dpp v68, v71 row_shr:12 row_mask:0xf bank_mask:0x8
	v_mov_b32_dpp v64, v67 row_shr:12 row_mask:0xf bank_mask:0x8
	v_mov_b32_dpp v60, v63 row_shr:12 row_mask:0xf bank_mask:0x8
	v_mov_b32_dpp v52, v55 row_shr:12 row_mask:0xf bank_mask:0x8
	v_mov_b32_dpp v48, v51 row_shr:12 row_mask:0xf bank_mask:0x8
	v_mov_b32_dpp v56, v59 row_shr:12 row_mask:0xf bank_mask:0x8
	s_waitcnt lgkmcnt(15)
	v_lshrrev_b32_e32 v152, 10, v136
	v_and_or_b32 v152, v152, s8, v112
	s_waitcnt lgkmcnt(14)
	v_lshrrev_b32_e32 v153, 10, v137
	v_and_or_b32 v153, v153, s8, v112
	s_waitcnt lgkmcnt(13)
	v_lshrrev_b32_e32 v154, 10, v138
	v_and_or_b32 v154, v154, s8, v112
	s_waitcnt lgkmcnt(12)
	v_lshrrev_b32_e32 v155, 10, v139
	v_and_or_b32 v155, v155, s8, v112
	s_waitcnt lgkmcnt(11)
	v_lshrrev_b32_e32 v156, 10, v140
	v_and_or_b32 v156, v156, s8, v112
	s_waitcnt lgkmcnt(10)
	v_lshrrev_b32_e32 v157, 10, v141
	v_and_or_b32 v157, v157, s8, v112
	s_waitcnt lgkmcnt(9)
	v_lshrrev_b32_e32 v158, 10, v142
	v_and_or_b32 v158, v158, s8, v112
	s_waitcnt lgkmcnt(8)
	v_lshrrev_b32_e32 v159, 10, v143
	v_and_or_b32 v159, v159, s8, v112
	s_waitcnt lgkmcnt(7)
	v_lshrrev_b32_e32 v160, 10, v144
	v_and_or_b32 v160, v160, s8, v112
	s_waitcnt lgkmcnt(6)
	v_lshrrev_b32_e32 v161, 10, v145
	v_and_or_b32 v161, v161, s8, v112
	s_waitcnt lgkmcnt(5)
	v_lshrrev_b32_e32 v162, 10, v146
	v_and_or_b32 v162, v162, s8, v112
	s_waitcnt lgkmcnt(4)
	v_lshrrev_b32_e32 v163, 10, v147
	v_and_or_b32 v163, v163, s8, v112
	s_waitcnt lgkmcnt(3)
	v_lshrrev_b32_e32 v164, 10, v148
	v_and_or_b32 v164, v164, s8, v112
	s_waitcnt lgkmcnt(2)
	v_lshrrev_b32_e32 v165, 10, v149
	v_and_or_b32 v165, v165, s8, v112
	s_waitcnt lgkmcnt(1)
	v_lshrrev_b32_e32 v166, 10, v150
	v_and_or_b32 v166, v166, s8, v112
	s_waitcnt lgkmcnt(0)
	v_lshrrev_b32_e32 v167, 10, v151
	v_and_or_b32 v167, v167, s8, v112
	ds_read_b32 v152, v152
	ds_read_b32 v153, v153
	ds_read_b32 v154, v154
	ds_read_b32 v155, v155
	ds_read_b32 v156, v156
	ds_read_b32 v157, v157
	ds_read_b32 v158, v158
	ds_read_b32 v159, v159
	ds_read_b32 v160, v160
	ds_read_b32 v161, v161
	ds_read_b32 v162, v162
	ds_read_b32 v163, v163
	ds_read_b32 v164, v164
	ds_read_b32 v165, v165
	ds_read_b32 v166, v166
	ds_read_b32 v167, v167
	s_waitcnt lgkmcnt(15)
	v_fmac_f32_e32 v152, 0x3e000000, v108
	v_cmp_lt_u32_e64 s[20:21], s45, v136
	s_waitcnt lgkmcnt(14)
	v_fmac_f32_e32 v153, 0x3e000000, v104
	v_cmp_lt_u32_e64 s[8:9], s45, v137
	v_cndmask_b32_e64 v110, v168, v152, s[20:21]
	s_waitcnt lgkmcnt(13)
	v_fmac_f32_e32 v154, 0x3e000000, v100
	v_cmp_lt_u32_e64 s[20:21], s45, v138
	v_cndmask_b32_e64 v109, v168, v153, s[8:9]
	s_waitcnt lgkmcnt(12)
	v_fmac_f32_e32 v155, 0x3e000000, v96
	v_cmp_lt_u32_e64 s[8:9], s45, v139
	v_cndmask_b32_e64 v102, v168, v154, s[20:21]
	s_waitcnt lgkmcnt(11)
	v_fmac_f32_e32 v156, 0x3e000000, v92
	v_cmp_lt_u32_e64 s[20:21], s45, v140
	v_cndmask_b32_e64 v101, v168, v155, s[8:9]
	s_waitcnt lgkmcnt(10)
	v_fmac_f32_e32 v157, 0x3e000000, v88
	v_cmp_lt_u32_e64 s[8:9], s45, v141
	v_cndmask_b32_e64 v94, v168, v156, s[20:21]
	s_waitcnt lgkmcnt(9)
	v_fmac_f32_e32 v158, 0x3e000000, v84
	v_cmp_lt_u32_e64 s[20:21], s45, v142
	v_cndmask_b32_e64 v93, v168, v157, s[8:9]
	s_waitcnt lgkmcnt(8)
	v_fmac_f32_e32 v159, 0x3e000000, v80
	v_cmp_lt_u32_e64 s[8:9], s45, v143
	v_cndmask_b32_e64 v86, v168, v158, s[20:21]
	s_waitcnt lgkmcnt(7)
	v_fmac_f32_e32 v160, 0x3e000000, v76
	v_cmp_lt_u32_e64 s[20:21], s45, v144
	v_cndmask_b32_e64 v85, v168, v159, s[8:9]
	s_waitcnt lgkmcnt(6)
	v_fmac_f32_e32 v161, 0x3e000000, v72
	v_cmp_lt_u32_e64 s[8:9], s45, v145
	v_cndmask_b32_e64 v78, v168, v160, s[20:21]
	s_waitcnt lgkmcnt(5)
	v_fmac_f32_e32 v162, 0x3e000000, v68
	v_cmp_lt_u32_e64 s[20:21], s45, v146
	v_cndmask_b32_e64 v77, v168, v161, s[8:9]
	s_waitcnt lgkmcnt(4)
	v_fmac_f32_e32 v163, 0x3e000000, v64
	v_cmp_lt_u32_e64 s[8:9], s45, v147
	v_cndmask_b32_e64 v70, v168, v162, s[20:21]
	s_waitcnt lgkmcnt(3)
	v_fmac_f32_e32 v164, 0x3e000000, v60
	v_cmp_lt_u32_e64 s[20:21], s45, v148
	v_cndmask_b32_e64 v69, v168, v163, s[8:9]
	s_waitcnt lgkmcnt(2)
	v_fmac_f32_e32 v165, 0x3e000000, v52
	v_cmp_lt_u32_e64 s[8:9], s45, v149
	v_cndmask_b32_e64 v62, v168, v164, s[20:21]
	s_waitcnt lgkmcnt(1)
	v_fmac_f32_e32 v166, 0x3e000000, v48
	v_cmp_lt_u32_e64 s[20:21], s45, v150
	v_cndmask_b32_e64 v61, v168, v165, s[8:9]
	s_waitcnt lgkmcnt(0)
	v_fmac_f32_e32 v167, 0x3e000000, v56
	v_cmp_lt_u32_e64 s[8:9], s45, v151
	v_cndmask_b32_e64 v50, v168, v166, s[20:21]
	s_nop 1
	v_cndmask_b32_e64 v49, v168, v167, s[8:9]
	v_max3_f32 v48, v110, s46, v109
	v_max3_f32 v48, v48, v102, v101
	v_max3_f32 v48, v48, v94, v93
	v_max3_f32 v48, v48, v86, v85
	v_max3_f32 v48, v48, v78, v77
	v_max3_f32 v48, v48, v70, v69
	v_max3_f32 v48, v48, v62, v61
	v_max3_f32 v48, v48, v50, v49
	v_mov_b32_e32 v51, v113
	v_mov_b32_e32 v68, v113
	v_bfe_u32 v98, v120, 4, 2
	v_mov_b32_dpp v51, v48 row_ror:4 row_mask:0xf bank_mask:0xf
	v_max_f32_e32 v51, v51, v51
	v_max_f32_e32 v48, v48, v51
	v_mov_b32_e32 v51, v113
	v_lshrrev_b32_e32 v100, 2, v116
	v_lshl_or_b32 v98, v98, 2, v100
	v_mov_b32_dpp v51, v48 row_ror:8 row_mask:0xf bank_mask:0xf
	v_max_f32_e32 v51, v51, v51
	v_max_f32_e32 v48, v48, v51
	v_mov_b32_e32 v51, v48
	s_nop 1
	v_permlane16_swap_b32_e32 v48, v51
	v_max_f32_e32 v51, v51, v51
	v_max_f32_e32 v48, v48, v48
	v_max_f32_e32 v48, v48, v51
	v_mov_b32_e32 v51, v48
	s_nop 1
	v_permlane32_swap_b32_e32 v48, v51
	v_max_f32_e32 v51, v51, v51
	v_max_f32_e32 v48, v48, v48
	v_max_f32_e32 v48, v48, v51
	v_sub_f32_e32 v51, v110, v48
	v_mul_f32_e32 v51, 0x3fb8aa3b, v51
	v_sub_f32_e32 v52, v109, v48
	v_exp_f32_e32 v51, v51
	v_mul_f32_e32 v52, 0x3fb8aa3b, v52
	v_sub_f32_e32 v53, v102, v48
	v_exp_f32_e32 v52, v52
	v_mul_f32_e32 v53, 0x3fb8aa3b, v53
	v_sub_f32_e32 v54, v101, v48
	v_exp_f32_e32 v53, v53
	v_mul_f32_e32 v54, 0x3fb8aa3b, v54
	v_sub_f32_e32 v56, v94, v48
	v_exp_f32_e32 v54, v54
	v_mul_f32_e32 v56, 0x3fb8aa3b, v56
	v_sub_f32_e32 v57, v93, v48
	v_add_f32_e32 v55, 0, v51
	v_exp_f32_e32 v56, v56
	v_mul_f32_e32 v57, 0x3fb8aa3b, v57
	v_sub_f32_e32 v58, v86, v48
	v_add_f32_e32 v55, v52, v55
	v_exp_f32_e32 v57, v57
	v_mul_f32_e32 v58, 0x3fb8aa3b, v58
	v_sub_f32_e32 v59, v85, v48
	v_add_f32_e32 v55, v53, v55
	v_exp_f32_e32 v58, v58
	v_mul_f32_e32 v59, 0x3fb8aa3b, v59
	v_sub_f32_e32 v60, v78, v48
	v_add_f32_e32 v55, v54, v55
	v_exp_f32_e32 v59, v59
	v_mul_f32_e32 v60, 0x3fb8aa3b, v60
	v_sub_f32_e32 v63, v77, v48
	v_sub_f32_e32 v64, v70, v48
	v_add_f32_e32 v55, v56, v55
	v_exp_f32_e32 v60, v60
	v_mul_f32_e32 v63, 0x3fb8aa3b, v63
	v_mul_f32_e32 v64, 0x3fb8aa3b, v64
	v_add_f32_e32 v55, v57, v55
	v_exp_f32_e32 v63, v63
	v_exp_f32_e32 v101, v64
	v_sub_f32_e32 v64, v69, v48
	v_add_f32_e32 v55, v58, v55
	v_mul_f32_e32 v64, 0x3fb8aa3b, v64
	v_sub_f32_e32 v62, v62, v48
	v_add_f32_e32 v55, v59, v55
	v_exp_f32_e32 v102, v64
	v_mul_f32_e32 v62, 0x3fb8aa3b, v62
	v_sub_f32_e32 v61, v61, v48
	v_add_f32_e32 v55, v60, v55
	v_exp_f32_e32 v103, v62
	v_mul_f32_e32 v61, 0x3fb8aa3b, v61
	v_sub_f32_e32 v50, v50, v48
	v_add_f32_e32 v55, v63, v55
	v_exp_f32_e32 v104, v61
	v_mul_f32_e32 v50, 0x3fb8aa3b, v50
	v_sub_f32_e32 v48, v49, v48
	v_add_f32_e32 v55, v101, v55
	v_exp_f32_e32 v105, v50
	v_mul_f32_e32 v48, 0x3fb8aa3b, v48
	v_add_f32_e32 v55, v102, v55
	v_exp_f32_e32 v106, v48
	v_add_f32_e32 v48, v103, v55
	v_add_f32_e32 v48, v104, v48
	v_add_f32_e32 v48, v105, v48
	v_add_f32_e32 v48, v106, v48
	v_mov_b32_e32 v50, v113
	v_mov_b32_e32 v55, v113
	v_add_f32_dpp v48, v48, v48 row_ror:4 row_mask:0xf bank_mask:0xf bound_ctrl:1
	v_mov_b32_e32 v61, v113
	v_mov_b32_dpp v50, v51 row_shl:8 row_mask:0xf bank_mask:0x1 bound_ctrl:1
	v_add_f32_dpp v48, v48, v48 row_ror:8 row_mask:0xf bank_mask:0xf bound_ctrl:1
	v_mov_b32_e32 v49, v48
	s_nop 1
	v_permlane16_swap_b32_e32 v48, v49
	v_add_f32_e32 v96, v48, v49
	v_mov_b32_e32 v49, v113
	v_cndmask_b32_e32 v48, 0, v51, vcc
	v_mov_b32_dpp v55, v51 row_shl:12 row_mask:0xf bank_mask:0x1 bound_ctrl:1
	v_mov_b32_dpp v49, v51 row_shl:4 row_mask:0xf bank_mask:0x1 bound_ctrl:1
	v_cndmask_b32_e32 v51, 0, v52, vcc
	v_mov_b32_dpp v61, v52 row_shl:4 row_mask:0xf bank_mask:0x1 bound_ctrl:1
	v_mov_b32_e32 v62, v113
	v_mov_b32_e32 v64, v113
	v_cvt_pk_bf16_f32 v76, v48, v49
	v_cvt_pk_bf16_f32 v77, v50, v55
	v_cvt_pk_bf16_f32 v78, v51, v61
	v_mov_b32_e32 v49, v113
	v_mov_b32_e32 v50, v113
	v_mov_b32_e32 v51, v113
	v_mov_b32_dpp v62, v52 row_shl:8 row_mask:0xf bank_mask:0x1 bound_ctrl:1
	v_mov_b32_dpp v64, v52 row_shl:12 row_mask:0xf bank_mask:0x1 bound_ctrl:1
	v_cndmask_b32_e32 v48, 0, v53, vcc
	v_mov_b32_dpp v49, v53 row_shl:4 row_mask:0xf bank_mask:0x1 bound_ctrl:1
	v_mov_b32_dpp v50, v53 row_shl:8 row_mask:0xf bank_mask:0x1 bound_ctrl:1
	v_mov_b32_dpp v51, v53 row_shl:12 row_mask:0xf bank_mask:0x1 bound_ctrl:1
	v_cvt_pk_bf16_f32 v79, v62, v64
	v_mov_b32_e32 v53, v113
	v_cvt_pk_bf16_f32 v64, v48, v49
	v_cvt_pk_bf16_f32 v65, v50, v51
	v_mov_b32_e32 v49, v113
	v_mov_b32_e32 v50, v113
	v_mov_b32_e32 v51, v113
	v_cndmask_b32_e32 v52, 0, v54, vcc
	v_mov_b32_dpp v53, v54 row_shl:4 row_mask:0xf bank_mask:0x1 bound_ctrl:1
	v_cndmask_b32_e32 v48, 0, v56, vcc
	v_mov_b32_dpp v49, v56 row_shl:4 row_mask:0xf bank_mask:0x1 bound_ctrl:1
	v_mov_b32_dpp v50, v56 row_shl:8 row_mask:0xf bank_mask:0x1 bound_ctrl:1
	v_mov_b32_dpp v51, v56 row_shl:12 row_mask:0xf bank_mask:0x1 bound_ctrl:1
	v_cvt_pk_bf16_f32 v66, v52, v53
	v_cvt_pk_bf16_f32 v52, v48, v49
	v_cvt_pk_bf16_f32 v53, v50, v51
	v_mov_b32_e32 v51, v113
	ds_read2_b32 v[48:49], v119 offset0:96 offset1:104
	v_cndmask_b32_e32 v50, 0, v58, vcc
	v_mov_b32_dpp v51, v58 row_shl:4 row_mask:0xf bank_mask:0x1 bound_ctrl:1
	v_cvt_pk_bf16_f32 v72, v50, v51
	ds_read2_b32 v[50:51], v119 offset0:112 offset1:120
	s_waitcnt lgkmcnt(1)
	v_lshlrev_b32_e32 v48, 9, v48
	v_and_or_b32 v48, v48, s43, v118
	v_lshlrev_b32_e32 v49, 9, v49
	v_and_or_b32 v49, v49, s43, v118
	global_load_dwordx4 v[80:83], v48, s[18:19]
	global_load_dwordx4 v[84:87], v49, s[18:19]
	s_waitcnt lgkmcnt(0)
	v_lshlrev_b32_e32 v48, 9, v50
	v_and_or_b32 v48, v48, s43, v118
	v_lshlrev_b32_e32 v49, 9, v51
	v_and_or_b32 v49, v49, s43, v118
	global_load_dwordx4 v[88:91], v48, s[18:19]
	global_load_dwordx4 v[92:95], v49, s[18:19]
	v_mov_b32_e32 v55, v113
	v_mov_b32_e32 v61, v113
	v_mov_b32_e32 v56, v113
	v_mov_b32_dpp v55, v54 row_shl:8 row_mask:0xf bank_mask:0x1 bound_ctrl:1
	v_mov_b32_dpp v61, v54 row_shl:12 row_mask:0xf bank_mask:0x1 bound_ctrl:1
	v_cvt_pk_bf16_f32 v67, v55, v61
	v_mov_b32_e32 v55, v113
	v_mov_b32_e32 v61, v113
	v_cndmask_b32_e32 v54, 0, v57, vcc
	v_mov_b32_dpp v55, v57 row_shl:4 row_mask:0xf bank_mask:0x1 bound_ctrl:1
	v_mov_b32_dpp v56, v57 row_shl:8 row_mask:0xf bank_mask:0x1 bound_ctrl:1
	v_mov_b32_dpp v61, v57 row_shl:12 row_mask:0xf bank_mask:0x1 bound_ctrl:1
	v_cvt_pk_bf16_f32 v54, v54, v55
	v_cvt_pk_bf16_f32 v55, v56, v61
	v_mov_b32_e32 v56, v113
	v_mov_b32_e32 v57, v113
	v_mov_b32_e32 v61, v113
	v_mov_b32_dpp v56, v58 row_shl:8 row_mask:0xf bank_mask:0x1 bound_ctrl:1
	v_mov_b32_dpp v57, v58 row_shl:12 row_mask:0xf bank_mask:0x1 bound_ctrl:1
	v_cndmask_b32_e32 v58, 0, v59, vcc
	v_mov_b32_dpp v61, v59 row_shl:4 row_mask:0xf bank_mask:0x1 bound_ctrl:1
	v_mov_b32_e32 v62, v113
	v_mov_b32_dpp v68, v59 row_shl:12 row_mask:0xf bank_mask:0x1 bound_ctrl:1
	v_cvt_pk_bf16_f32 v74, v58, v61
	v_mov_b32_dpp v62, v59 row_shl:8 row_mask:0xf bank_mask:0x1 bound_ctrl:1
	v_mov_b32_e32 v49, v113
	v_mov_b32_e32 v50, v113
	v_mov_b32_e32 v51, v113
	v_mov_b32_e32 v58, v113
	v_mov_b32_e32 v59, v113
	v_cvt_pk_bf16_f32 v73, v56, v57
	v_cndmask_b32_e32 v48, 0, v60, vcc
	v_mov_b32_dpp v49, v60 row_shl:4 row_mask:0xf bank_mask:0x1 bound_ctrl:1
	v_mov_b32_dpp v50, v60 row_shl:8 row_mask:0xf bank_mask:0x1 bound_ctrl:1
	v_mov_b32_dpp v51, v60 row_shl:12 row_mask:0xf bank_mask:0x1 bound_ctrl:1
	v_mov_b32_e32 v57, v113
	v_mov_b32_dpp v58, v63 row_shl:8 row_mask:0xf bank_mask:0x1 bound_ctrl:1
	v_mov_b32_dpp v59, v63 row_shl:12 row_mask:0xf bank_mask:0x1 bound_ctrl:1
	v_cvt_pk_bf16_f32 v75, v62, v68
	v_cndmask_b32_e32 v56, 0, v63, vcc
	v_mov_b32_dpp v57, v63 row_shl:4 row_mask:0xf bank_mask:0x1 bound_ctrl:1
	v_cvt_pk_bf16_f32 v68, v48, v49
	v_cvt_pk_bf16_f32 v69, v50, v51
	v_cvt_pk_bf16_f32 v71, v58, v59
	v_mov_b32_e32 v49, v113
	v_mov_b32_e32 v50, v113
	v_mov_b32_e32 v51, v113
	v_mov_b32_e32 v58, v113
	v_mov_b32_e32 v59, v113
	v_cvt_pk_bf16_f32 v70, v56, v57
	v_cndmask_b32_e32 v48, 0, v101, vcc
	v_mov_b32_dpp v49, v101 row_shl:4 row_mask:0xf bank_mask:0x1 bound_ctrl:1
	v_mov_b32_dpp v50, v101 row_shl:8 row_mask:0xf bank_mask:0x1 bound_ctrl:1
	v_mov_b32_dpp v51, v101 row_shl:12 row_mask:0xf bank_mask:0x1 bound_ctrl:1
	v_mov_b32_e32 v57, v113
	v_mov_b32_dpp v58, v102 row_shl:8 row_mask:0xf bank_mask:0x1 bound_ctrl:1
	v_mov_b32_dpp v59, v102 row_shl:12 row_mask:0xf bank_mask:0x1 bound_ctrl:1
	v_cndmask_b32_e32 v56, 0, v102, vcc
	v_mov_b32_dpp v57, v102 row_shl:4 row_mask:0xf bank_mask:0x1 bound_ctrl:1
	v_cvt_pk_bf16_f32 v60, v48, v49
	v_cvt_pk_bf16_f32 v61, v50, v51
	v_cvt_pk_bf16_f32 v63, v58, v59
	v_mov_b32_e32 v49, v113
	v_mov_b32_e32 v50, v113
	v_mov_b32_e32 v51, v113
	v_mov_b32_e32 v59, v113
	v_mov_b32_e32 v101, v113
	v_mov_b32_e32 v102, v113
	v_cndmask_b32_e32 v48, 0, v103, vcc
	v_mov_b32_dpp v49, v103 row_shl:4 row_mask:0xf bank_mask:0x1 bound_ctrl:1
	v_mov_b32_dpp v50, v103 row_shl:8 row_mask:0xf bank_mask:0x1 bound_ctrl:1
	v_mov_b32_dpp v51, v103 row_shl:12 row_mask:0xf bank_mask:0x1 bound_ctrl:1
	v_cndmask_b32_e32 v58, 0, v104, vcc
	v_mov_b32_dpp v59, v104 row_shl:4 row_mask:0xf bank_mask:0x1 bound_ctrl:1
	v_mov_b32_dpp v101, v104 row_shl:8 row_mask:0xf bank_mask:0x1 bound_ctrl:1
	v_mov_b32_dpp v102, v104 row_shl:12 row_mask:0xf bank_mask:0x1 bound_ctrl:1
	v_cvt_pk_bf16_f32 v62, v56, v57
	v_cvt_pk_bf16_f32 v56, v48, v49
	v_cvt_pk_bf16_f32 v57, v50, v51
	v_cvt_pk_bf16_f32 v58, v58, v59
	v_cvt_pk_bf16_f32 v59, v101, v102
	v_mov_b32_e32 v49, v113
	v_mov_b32_e32 v50, v113
	v_mov_b32_e32 v51, v113
	v_mov_b32_e32 v102, v113
	v_mov_b32_e32 v103, v113
	v_mov_b32_e32 v104, v113
	v_lshlrev_b32_e32 v100, 3, v120
	v_mov_b32_e32 v97, v96
	v_cndmask_b32_e32 v48, 0, v105, vcc
	v_mov_b32_dpp v49, v105 row_shl:4 row_mask:0xf bank_mask:0x1 bound_ctrl:1
	v_mov_b32_dpp v50, v105 row_shl:8 row_mask:0xf bank_mask:0x1 bound_ctrl:1
	v_mov_b32_dpp v51, v105 row_shl:12 row_mask:0xf bank_mask:0x1 bound_ctrl:1
	v_cndmask_b32_e32 v101, 0, v106, vcc
	v_mov_b32_dpp v102, v106 row_shl:4 row_mask:0xf bank_mask:0x1 bound_ctrl:1
	v_mov_b32_dpp v103, v106 row_shl:8 row_mask:0xf bank_mask:0x1 bound_ctrl:1
	v_mov_b32_dpp v104, v106 row_shl:12 row_mask:0xf bank_mask:0x1 bound_ctrl:1
	v_mul_u32_u24_e32 v98, 0xa0, v98
	v_and_b32_e32 v100, 24, v100
	v_mul_u32_u24_e32 v99, 0xa0, v122
	v_permlane32_swap_b32_e32 v96, v97
	v_cvt_pk_bf16_f32 v48, v48, v49
	v_cvt_pk_bf16_f32 v49, v50, v51
	v_cvt_pk_bf16_f32 v50, v101, v102
	v_cvt_pk_bf16_f32 v51, v103, v104
	v_add3_u32 v110, s47, v98, v100
	v_add_u32_e32 v111, v121, v99
	s_waitcnt vmcnt(15)
	ds_write_b128 v111, v[32:35] offset:1024
	s_waitcnt vmcnt(14)
	ds_write_b128 v111, v[36:39] offset:2304
	s_waitcnt vmcnt(13)
	ds_write_b128 v111, v[40:43] offset:3584
	s_waitcnt vmcnt(12)
	ds_write_b128 v111, v[44:47] offset:4864
	ds_read_b64_tr_b16 v[34:35], v110 offset:3584
	ds_read_b64_tr_b16 v[32:33], v110 offset:1024
	ds_read_b64_tr_b16 v[36:37], v110 offset:1056
	ds_read_b64_tr_b16 v[40:41], v110 offset:1088
	ds_read_b64_tr_b16 v[44:45], v110 offset:1120
	ds_read_b64_tr_b16 v[38:39], v110 offset:3616
	ds_read_b64_tr_b16 v[42:43], v110 offset:3648
	ds_read_b64_tr_b16 v[46:47], v110 offset:3680
	ds_read2_b32 v[98:99], v119 offset0:128 offset1:136
	ds_read2_b32 v[106:107], v119 offset0:144 offset1:152
	s_waitcnt lgkmcnt(8)
	v_mfma_f32_16x16x32_bf16 v[32:35], v[76:79], v[32:35], 0
	s_waitcnt lgkmcnt(1)
	v_lshlrev_b32_e32 v98, 9, v98
	v_and_or_b32 v108, v98, s43, v118
	v_lshlrev_b32_e32 v98, 9, v99
	s_waitcnt lgkmcnt(0)
	v_lshlrev_b32_e32 v106, 9, v106
	v_and_or_b32 v109, v98, s43, v118
	v_and_or_b32 v112, v106, s43, v118
	v_lshlrev_b32_e32 v106, 9, v107
	global_load_dwordx4 v[98:101], v108, s[18:19]
	global_load_dwordx4 v[102:105], v109, s[18:19]
	v_and_or_b32 v124, v106, s43, v118
	global_load_dwordx4 v[106:109], v112, s[18:19]
	global_load_dwordx4 v[120:123], v124, s[18:19]
	v_mfma_f32_16x16x32_bf16 v[36:39], v[76:79], v[36:39], 0
	v_mfma_f32_16x16x32_bf16 v[40:43], v[76:79], v[40:43], 0
	v_mfma_f32_16x16x32_bf16 v[44:47], v[76:79], v[44:47], 0
	s_waitcnt vmcnt(15)
	ds_write_b128 v111, v[16:19] offset:1024
	s_waitcnt vmcnt(14)
	ds_write_b128 v111, v[20:23] offset:2304
	s_waitcnt vmcnt(13)
	ds_write_b128 v111, v[24:27] offset:3584
	s_waitcnt vmcnt(12)
	ds_write_b128 v111, v[28:31] offset:4864
	ds_read_b64_tr_b16 v[18:19], v110 offset:3584
	ds_read_b64_tr_b16 v[16:17], v110 offset:1024
	ds_read_b64_tr_b16 v[20:21], v110 offset:1056
	ds_read_b64_tr_b16 v[24:25], v110 offset:1088
	ds_read_b64_tr_b16 v[28:29], v110 offset:1120
	ds_read_b64_tr_b16 v[22:23], v110 offset:3616
	ds_read_b64_tr_b16 v[26:27], v110 offset:3648
	ds_read_b64_tr_b16 v[30:31], v110 offset:3680
	s_waitcnt lgkmcnt(6)
	v_mfma_f32_16x16x32_bf16 v[16:19], v[64:67], v[16:19], v[32:35]
	s_waitcnt lgkmcnt(1)
	v_mfma_f32_16x16x32_bf16 v[24:27], v[64:67], v[24:27], v[40:43]
	s_nop 0
	ds_read2_b32 v[32:33], v119 offset0:160 offset1:168
	s_waitcnt lgkmcnt(0)
	v_lshlrev_b32_e32 v32, 9, v32
	ds_read2_b32 v[40:41], v119 offset0:176 offset1:184
	v_lshlrev_b32_e32 v33, 9, v33
	v_mfma_f32_16x16x32_bf16 v[20:23], v[64:67], v[20:23], v[36:39]
	v_and_or_b32 v32, v32, s43, v118
	s_waitcnt lgkmcnt(0)
	v_lshlrev_b32_e32 v40, 9, v40
	v_and_or_b32 v36, v33, s43, v118
	v_and_or_b32 v112, v40, s43, v118
	v_lshlrev_b32_e32 v40, 9, v41
	global_load_dwordx4 v[32:35], v32, s[18:19]
	s_nop 0
	global_load_dwordx4 v[36:39], v36, s[18:19]
	v_and_or_b32 v124, v40, s43, v118
	global_load_dwordx4 v[40:43], v112, s[18:19]
	global_load_dwordx4 v[76:79], v124, s[18:19]
	v_mfma_f32_16x16x32_bf16 v[28:31], v[64:67], v[28:31], v[44:47]
	s_waitcnt vmcnt(15)
	ds_write_b128 v111, v[0:3] offset:1024
	s_waitcnt vmcnt(14)
	ds_write_b128 v111, v[4:7] offset:2304
	s_waitcnt vmcnt(13)
	ds_write_b128 v111, v[8:11] offset:3584
	s_waitcnt vmcnt(12)
	ds_write_b128 v111, v[12:15] offset:4864
	ds_read_b64_tr_b16 v[2:3], v110 offset:3584
	ds_read_b64_tr_b16 v[0:1], v110 offset:1024
	ds_read_b64_tr_b16 v[4:5], v110 offset:1056
	ds_read_b64_tr_b16 v[8:9], v110 offset:1088
	ds_read_b64_tr_b16 v[12:13], v110 offset:1120
	ds_read_b64_tr_b16 v[6:7], v110 offset:3616
	ds_read_b64_tr_b16 v[10:11], v110 offset:3648
	ds_read_b64_tr_b16 v[14:15], v110 offset:3680
	s_waitcnt lgkmcnt(6)
	v_mfma_f32_16x16x32_bf16 v[0:3], v[52:55], v[0:3], v[16:19]
	s_waitcnt lgkmcnt(1)
	v_mfma_f32_16x16x32_bf16 v[8:11], v[52:55], v[8:11], v[24:27]
	s_nop 0
	ds_read2_b32 v[16:17], v119 offset0:192 offset1:200
	s_waitcnt lgkmcnt(0)
	v_lshlrev_b32_e32 v16, 9, v16
	ds_read2_b32 v[24:25], v119 offset0:208 offset1:216
	v_lshlrev_b32_e32 v17, 9, v17
	v_mfma_f32_16x16x32_bf16 v[4:7], v[52:55], v[4:7], v[20:23]
	v_and_or_b32 v16, v16, s43, v118
	s_waitcnt lgkmcnt(0)
	v_lshlrev_b32_e32 v24, 9, v24
	v_and_or_b32 v20, v17, s43, v118
	v_and_or_b32 v64, v24, s43, v118
	v_lshlrev_b32_e32 v24, 9, v25
	global_load_dwordx4 v[16:19], v16, s[18:19]
	s_nop 0
	global_load_dwordx4 v[20:23], v20, s[18:19]
	v_and_or_b32 v65, v24, s43, v118
	global_load_dwordx4 v[24:27], v64, s[18:19]
	global_load_dwordx4 v[44:47], v65, s[18:19]
	v_mfma_f32_16x16x32_bf16 v[12:15], v[52:55], v[12:15], v[28:31]
	s_waitcnt vmcnt(15)
	ds_write_b128 v111, v[80:83] offset:1024
	s_waitcnt vmcnt(14)
	ds_write_b128 v111, v[84:87] offset:2304
	s_waitcnt vmcnt(13)
	ds_write_b128 v111, v[88:91] offset:3584
	s_waitcnt vmcnt(12)
	ds_write_b128 v111, v[92:95] offset:4864
	ds_read_b64_tr_b16 v[30:31], v110 offset:3584
	ds_read_b64_tr_b16 v[28:29], v110 offset:1024
	ds_read_b64_tr_b16 v[52:53], v110 offset:1056
	ds_read_b64_tr_b16 v[64:65], v110 offset:1088
	ds_read_b64_tr_b16 v[80:81], v110 offset:1120
	ds_read_b64_tr_b16 v[54:55], v110 offset:3616
	ds_read_b64_tr_b16 v[66:67], v110 offset:3648
	ds_read_b64_tr_b16 v[82:83], v110 offset:3680
	s_waitcnt lgkmcnt(6)
	v_mfma_f32_16x16x32_bf16 v[0:3], v[72:75], v[28:31], v[0:3]
	ds_read2_b32 v[28:29], v119 offset0:224 offset1:232
	s_waitcnt lgkmcnt(0)
	v_lshlrev_b32_e32 v28, 9, v28
	v_mfma_f32_16x16x32_bf16 v[8:11], v[72:75], v[64:67], v[8:11]
	ds_read2_b32 v[64:65], v119 offset0:240 offset1:248
	v_and_or_b32 v66, v28, s43, v118
	v_lshlrev_b32_e32 v28, 9, v29
	v_and_or_b32 v67, v28, s43, v118
	v_mfma_f32_16x16x32_bf16 v[4:7], v[72:75], v[52:55], v[4:7]
	s_waitcnt lgkmcnt(0)
	v_lshlrev_b32_e32 v64, 9, v64
	v_and_or_b32 v88, v64, s43, v118
	v_lshlrev_b32_e32 v64, 9, v65
	global_load_dwordx4 v[28:31], v66, s[18:19]
	global_load_dwordx4 v[52:55], v67, s[18:19]
	v_and_or_b32 v89, v64, s43, v118
	global_load_dwordx4 v[64:67], v88, s[18:19]
	global_load_dwordx4 v[84:87], v89, s[18:19]
	v_mfma_f32_16x16x32_bf16 v[12:15], v[72:75], v[80:83], v[12:15]
	s_waitcnt vmcnt(15)
	ds_write_b128 v111, v[98:101] offset:1024
	s_waitcnt vmcnt(14)
	ds_write_b128 v111, v[102:105] offset:2304
	s_waitcnt vmcnt(13)
	ds_write_b128 v111, v[106:109] offset:3584
	s_waitcnt vmcnt(12)
	ds_write_b128 v111, v[120:123] offset:4864
	ds_read_b64_tr_b16 v[74:75], v110 offset:3584
	ds_read_b64_tr_b16 v[72:73], v110 offset:1024
	ds_read_b64_tr_b16 v[80:81], v110 offset:1056
	ds_read_b64_tr_b16 v[88:89], v110 offset:1088
	ds_read_b64_tr_b16 v[92:93], v110 offset:1120
	ds_read_b64_tr_b16 v[82:83], v110 offset:3616
	ds_read_b64_tr_b16 v[90:91], v110 offset:3648
	ds_read_b64_tr_b16 v[94:95], v110 offset:3680
	s_waitcnt lgkmcnt(6)
	v_mfma_f32_16x16x32_bf16 v[0:3], v[68:71], v[72:75], v[0:3]
	s_waitcnt lgkmcnt(2)
	v_mfma_f32_16x16x32_bf16 v[4:7], v[68:71], v[80:83], v[4:7]
	s_waitcnt lgkmcnt(1)
	v_mfma_f32_16x16x32_bf16 v[8:11], v[68:71], v[88:91], v[8:11]
	s_waitcnt lgkmcnt(0)
	v_mfma_f32_16x16x32_bf16 v[12:15], v[68:71], v[92:95], v[12:15]
	s_waitcnt vmcnt(11)
	ds_write_b128 v111, v[32:35] offset:1024
	s_waitcnt vmcnt(10)
	ds_write_b128 v111, v[36:39] offset:2304
	s_waitcnt vmcnt(9)
	ds_write_b128 v111, v[40:43] offset:3584
	s_waitcnt vmcnt(8)
	ds_write_b128 v111, v[76:79] offset:4864
	ds_read_b64_tr_b16 v[34:35], v110 offset:3584
	ds_read_b64_tr_b16 v[32:33], v110 offset:1024
	ds_read_b64_tr_b16 v[36:37], v110 offset:1056
	ds_read_b64_tr_b16 v[40:41], v110 offset:1088
	ds_read_b64_tr_b16 v[68:69], v110 offset:1120
	ds_read_b64_tr_b16 v[38:39], v110 offset:3616
	ds_read_b64_tr_b16 v[42:43], v110 offset:3648
	ds_read_b64_tr_b16 v[70:71], v110 offset:3680
	s_waitcnt lgkmcnt(6)
	v_mfma_f32_16x16x32_bf16 v[0:3], v[60:63], v[32:35], v[0:3]
	s_waitcnt lgkmcnt(2)
	v_mfma_f32_16x16x32_bf16 v[4:7], v[60:63], v[36:39], v[4:7]
	s_waitcnt lgkmcnt(1)
	v_mfma_f32_16x16x32_bf16 v[8:11], v[60:63], v[40:43], v[8:11]
	s_waitcnt lgkmcnt(0)
	v_mfma_f32_16x16x32_bf16 v[12:15], v[60:63], v[68:71], v[12:15]
	s_waitcnt vmcnt(7)
	ds_write_b128 v111, v[16:19] offset:1024
	s_waitcnt vmcnt(6)
	ds_write_b128 v111, v[20:23] offset:2304
	s_waitcnt vmcnt(5)
	ds_write_b128 v111, v[24:27] offset:3584
	s_waitcnt vmcnt(4)
	ds_write_b128 v111, v[44:47] offset:4864
	ds_read_b64_tr_b16 v[18:19], v110 offset:3584
	ds_read_b64_tr_b16 v[16:17], v110 offset:1024
	ds_read_b64_tr_b16 v[20:21], v110 offset:1056
	ds_read_b64_tr_b16 v[24:25], v110 offset:1088
	ds_read_b64_tr_b16 v[32:33], v110 offset:1120
	ds_read_b64_tr_b16 v[22:23], v110 offset:3616
	ds_read_b64_tr_b16 v[26:27], v110 offset:3648
	ds_read_b64_tr_b16 v[34:35], v110 offset:3680
	s_waitcnt lgkmcnt(6)
	v_mfma_f32_16x16x32_bf16 v[0:3], v[56:59], v[16:19], v[0:3]
	s_waitcnt lgkmcnt(2)
	v_mfma_f32_16x16x32_bf16 v[4:7], v[56:59], v[20:23], v[4:7]
	s_waitcnt lgkmcnt(1)
	v_mfma_f32_16x16x32_bf16 v[8:11], v[56:59], v[24:27], v[8:11]
	s_waitcnt lgkmcnt(0)
	v_mfma_f32_16x16x32_bf16 v[16:19], v[56:59], v[32:35], v[12:15]
	s_waitcnt vmcnt(3)
	ds_write_b128 v111, v[28:31] offset:1024
	s_waitcnt vmcnt(2)
	ds_write_b128 v111, v[52:55] offset:2304
	s_waitcnt vmcnt(1)
	ds_write_b128 v111, v[64:67] offset:3584
	s_waitcnt vmcnt(0)
	ds_write_b128 v111, v[84:87] offset:4864
	ds_read_b64_tr_b16 v[14:15], v110 offset:3584
	ds_read_b64_tr_b16 v[12:13], v110 offset:1024
	ds_read_b64_tr_b16 v[20:21], v110 offset:1056
	ds_read_b64_tr_b16 v[24:25], v110 offset:1088
	ds_read_b64_tr_b16 v[28:29], v110 offset:1120
	ds_read_b64_tr_b16 v[22:23], v110 offset:3616
	ds_read_b64_tr_b16 v[26:27], v110 offset:3648
	ds_read_b64_tr_b16 v[30:31], v110 offset:3680
	s_waitcnt lgkmcnt(6)
	v_mfma_f32_16x16x32_bf16 v[12:15], v[48:51], v[12:15], v[0:3]
	v_cmp_gt_u32_e32 vcc, 16, v117
	s_waitcnt lgkmcnt(1)
	v_mfma_f32_16x16x32_bf16 v[0:3], v[48:51], v[24:27], v[8:11]
	s_waitcnt lgkmcnt(0)
	v_mfma_f32_16x16x32_bf16 v[8:11], v[48:51], v[28:31], v[16:19]
	s_nop 2
	v_add_f32_e32 v19, v96, v97
	ds_bpermute_b32 v16, v114, v19
	ds_bpermute_b32 v17, v114, v19 offset:4
	ds_bpermute_b32 v18, v114, v19 offset:8
	ds_bpermute_b32 v19, v114, v19 offset:12
	v_mfma_f32_16x16x32_bf16 v[4:7], v[48:51], v[20:23], v[4:7]
	s_and_saveexec_b64 s[8:9], vcc
	s_cbranch_execz .LBB0_1251
	s_waitcnt lgkmcnt(0)
	v_div_scale_f32 v20, s[18:19], v19, v19, 1.0
	v_rcp_f32_e32 v21, v20
	v_div_scale_f32 v22, vcc, 1.0, v19, 1.0
	v_lshlrev_b32_e32 v112, 1, v116
	v_fma_f32 v23, -v20, v21, 1.0
	v_fmac_f32_e32 v21, v23, v21
	v_mul_f32_e32 v23, v22, v21
	v_fma_f32 v24, -v20, v23, v22
	v_fmac_f32_e32 v23, v24, v21
	v_fma_f32 v20, -v20, v23, v22
	v_div_scale_f32 v22, s[18:19], v18, v18, 1.0
	v_rcp_f32_e32 v24, v22
	v_div_fmas_f32 v20, v20, v21, v23
	v_div_fixup_f32 v19, v20, v19, 1.0
	v_fma_f32 v20, -v22, v24, 1.0
	v_fmac_f32_e32 v24, v20, v24
	v_div_scale_f32 v20, vcc, 1.0, v18, 1.0
	v_mul_f32_e32 v21, v20, v24
	v_fma_f32 v23, -v22, v21, v20
	v_fmac_f32_e32 v21, v23, v24
	v_fma_f32 v20, -v22, v21, v20
	v_div_scale_f32 v22, s[18:19], v17, v17, 1.0
	v_rcp_f32_e32 v23, v22
	v_div_fmas_f32 v20, v20, v24, v21
	v_div_fixup_f32 v18, v20, v18, 1.0
	v_fma_f32 v20, -v22, v23, 1.0
	v_fmac_f32_e32 v23, v20, v23
	v_div_scale_f32 v20, vcc, 1.0, v17, 1.0
	v_mul_f32_e32 v21, v20, v23
	v_fma_f32 v24, -v22, v21, v20
	v_fmac_f32_e32 v21, v24, v23
	v_fma_f32 v20, -v22, v21, v20
	v_div_scale_f32 v22, s[18:19], v16, v16, 1.0
	v_rcp_f32_e32 v24, v22
	v_div_fmas_f32 v20, v20, v23, v21
	v_div_fixup_f32 v20, v20, v17, 1.0
	v_fma_f32 v17, -v22, v24, 1.0
	v_fmac_f32_e32 v24, v17, v24
	v_div_scale_f32 v17, vcc, 1.0, v16, 1.0
	v_mul_f32_e32 v21, v17, v24
	v_fma_f32 v23, -v22, v21, v17
	v_fmac_f32_e32 v21, v23, v24
	v_fma_f32 v17, -v22, v21, v17
	v_div_fmas_f32 v17, v17, v24, v21
	v_div_fixup_f32 v21, v17, v16, 1.0
	v_lshl_add_u64 v[16:17], s[16:17], 0, v[112:113]
	v_mul_f32_e32 v0, v0, v21
	v_lshl_add_u64 v[16:17], v[16:17], 0, s[14:15]
	v_cvt_pk_bf16_f32 v0, v0, s0
	global_store_short v[16:17], v0, off offset:64
	v_mul_f32_e32 v0, v8, v21
	v_cvt_pk_bf16_f32 v0, v0, s0
	global_store_short v[16:17], v0, off offset:96
	v_mul_f32_e32 v0, v13, v20
	v_cvt_pk_bf16_f32 v0, v0, s0
	global_store_short v[16:17], v0, off offset:128
	v_mul_f32_e32 v0, v5, v20
	v_cvt_pk_bf16_f32 v0, v0, s0
	global_store_short v[16:17], v0, off offset:160
	v_mul_f32_e32 v0, v1, v20
	v_cvt_pk_bf16_f32 v0, v0, s0
	global_store_short v[16:17], v0, off offset:192
	v_mul_f32_e32 v0, v9, v20
	v_cvt_pk_bf16_f32 v0, v0, s0
	global_store_short v[16:17], v0, off offset:224
	v_mul_f32_e32 v0, v14, v18
	v_cvt_pk_bf16_f32 v0, v0, s0
	global_store_short v[16:17], v0, off offset:256
	v_mul_f32_e32 v0, v6, v18
	v_cvt_pk_bf16_f32 v0, v0, s0
	global_store_short v[16:17], v0, off offset:288
	v_mul_f32_e32 v0, v2, v18
	v_cvt_pk_bf16_f32 v0, v0, s0
	global_store_short v[16:17], v0, off offset:320
	v_mul_f32_e32 v0, v10, v18
	v_cvt_pk_bf16_f32 v0, v0, s0
	global_store_short v[16:17], v0, off offset:352
	v_mul_f32_e32 v0, v15, v19
	v_cvt_pk_bf16_f32 v0, v0, s0
	global_store_short v[16:17], v0, off offset:384
	v_mul_f32_e32 v0, v7, v19
	v_cvt_pk_bf16_f32 v0, v0, s0
	global_store_short v[16:17], v0, off offset:416
	v_mul_f32_e32 v0, v3, v19
	v_cvt_pk_bf16_f32 v0, v0, s0
	v_mul_f32_e32 v12, v12, v21
	v_mul_f32_e32 v4, v4, v21
	global_store_short v[16:17], v0, off offset:448
	v_mul_f32_e32 v0, v11, v19
	v_cvt_pk_bf16_f32 v12, v12, s0
	v_cvt_pk_bf16_f32 v4, v4, s0
	v_cvt_pk_bf16_f32 v0, v0, s0
	global_store_short v[16:17], v12, off
	global_store_short v[16:17], v4, off offset:32
	global_store_short v[16:17], v0, off offset:480
	s_branch .LBB0_1251
